# U rows re-pitched to 8 KB so every row panel stays XCD-local; runtime-verified XCD-local barriers at 5 of 8 phase seams; early invalidate
# speedup vs baseline: 1.0339x; 1.0080x over previous
; #define SEAM(k) do { if (IN(k) && IN((k) + 1)) { if (lo < 0) cg::this_grid().sync(); else xcd_barrier(bar); } } while (0)
;     __device__ bool next(int i, Unit& u) const {
;         long L = (long)i * G + c; u.half = 0;
;         if (split) { const int fr_ = nwg / G, rem = nwg - fr_ * G; if (i > fr_) return false; if (i == fr_) { L = (long)fr_ * G + (c % rem); u.half = 1 + c / rem; } }
;         if (L >= nwg) return false;
;         int wgid = (int)L; { const int q = nwg / NXCD, r = nwg % NXCD, xcd = wgid % NXCD, off = wgid / NXCD; wgid = (xcd < r ? xcd * (q + 1) : r * (q + 1) + (xcd - r) * q) + off; }
;         const int nig = WGM * nN, gid = wgid / nig, fm = gid * WGM, gsz = (nM - fm) < WGM ? (nM - fm) : WGM;
;         u.pm = fm + ((wgid % nig) % gsz); u.pn = (wgid % nig) / gsz; return true;
; __global__ void __launch_bounds__(NTHREADS, 2) mega_fwd(Args a) {
;     ...
;     const bool late_in_p1 = (G == 256) && IN(0) && IN(1);
;     if (IN(0)) { for (int rep = 0; rep < a.rep0; ++rep) p0_prologue(a, lds, G, late_in_p1); SEAM(0); }
;     if (IN(1)) {
;         if ((int)blockIdx.x >= G - 2) {
;             pg8::Gemm g{(const bf16_t*)(ws + WS_MEMN), (const bf16_t*)(ws + WS_WMKV), D, D, D, MEML, 512}; pg8::StaticOrder so; so.init(MEML, 512, 2, (int)blockIdx.x - (G - 2));
;             pg8::Epi E{}; E.mode = pg8::M_MEMKV; E.O = (bf16_t*)(ws + WS_KV); E.gains = (const float*)(ws + WS_GAINS);
;             pg8::gemm_phase(lds, g, so, E);
;         }
;         pg8::Gemm g{XB, (const bf16_t*)(ws + WS_W13_1), D, D, D, S, 2 * FF}; pg8::StaticOrder so; so.init(S, 2 * FF, G, (int)blockIdx.x);
.LBB0_249:
	s_mov_b32 s98, 1
	s_mov_b32 s99, 0
	s_load_dword s100, s[28:29], 0x84000
	s_waitcnt lgkmcnt(0)
	s_bcnt1_i32_b32 s101, s100
	s_cmp_eq_u32 s101, 1
	s_cselect_b32 s98, s98, 0
	s_or_b32 s99, s99, s100
	s_load_dword s100, s[28:29], 0x84004
	s_waitcnt lgkmcnt(0)
	s_bcnt1_i32_b32 s101, s100
	s_cmp_eq_u32 s101, 1
	s_cselect_b32 s98, s98, 0
	s_or_b32 s99, s99, s100
	s_load_dword s100, s[28:29], 0x84008
	s_waitcnt lgkmcnt(0)
	s_bcnt1_i32_b32 s101, s100
	s_cmp_eq_u32 s101, 1
	s_cselect_b32 s98, s98, 0
	s_or_b32 s99, s99, s100
	s_load_dword s100, s[28:29], 0x8400c
	s_waitcnt lgkmcnt(0)
	s_bcnt1_i32_b32 s101, s100
	s_cmp_eq_u32 s101, 1
	s_cselect_b32 s98, s98, 0
	s_or_b32 s99, s99, s100
	s_load_dword s100, s[28:29], 0x84010
	s_waitcnt lgkmcnt(0)
	s_bcnt1_i32_b32 s101, s100
	s_cmp_eq_u32 s101, 1
	s_cselect_b32 s98, s98, 0
	s_or_b32 s99, s99, s100
	s_load_dword s100, s[28:29], 0x84014
	s_waitcnt lgkmcnt(0)
	s_bcnt1_i32_b32 s101, s100
	s_cmp_eq_u32 s101, 1
	s_cselect_b32 s98, s98, 0
	s_or_b32 s99, s99, s100
	s_load_dword s100, s[28:29], 0x84018
	s_waitcnt lgkmcnt(0)
	s_bcnt1_i32_b32 s101, s100
	s_cmp_eq_u32 s101, 1
	s_cselect_b32 s98, s98, 0
	s_or_b32 s99, s99, s100
	s_load_dword s100, s[28:29], 0x8401c
	s_waitcnt lgkmcnt(0)
	s_bcnt1_i32_b32 s101, s100
	s_cmp_eq_u32 s101, 1
	s_cselect_b32 s98, s98, 0
	s_or_b32 s99, s99, s100
	s_bcnt1_i32_b32 s101, s99
	s_cmp_eq_u32 s101, 8
	s_cselect_b32 s98, s98, 0
	s_cmpk_eq_i32 s11, 0x100
	s_cselect_b32 s98, s98, 0
	s_add_u32 s8, s28, 0x3600000
	s_addc_u32 s9, s29, 0
	s_add_u32 s20, s28, 0x5600000
	s_addc_u32 s21, s29, 0
	s_cmp_lt_i32 s30, 2
	s_cselect_b64 s[2:3], -1, 0
	s_and_b64 s[2:3], s[2:3], s[68:69]
	s_andn2_b64 vcc, exec, s[2:3]
	s_cbranch_vccnz .LBB0_457
	s_add_i32 s2, s11, -2
	s_cmp_ge_i32 s10, s2
	s_cbranch_scc0 .LBB0_292
	s_add_u32 s4, s28, 0xdb00000
	s_addc_u32 s5, s29, 0
	s_add_u32 s6, s28, 0xdc00000
	s_addc_u32 s7, s29, 0
	s_sub_i32 s74, s10, s2
	s_cmp_lt_i32 s74, 2
	v_readfirstlane_b32 s12, v198
	s_mov_b64 s[14:15], 0
	s_mov_b64 s[16:17], 0
	s_mov_b64 s[18:19], 0
	s_mov_b64 s[22:23], 0
	s_cselect_b64 s[2:3], -1, 0
	s_cmp_gt_i32 s74, 1
	s_cbranch_scc1 .LBB0_253
	s_ashr_i32 s13, s74, 31
	s_lshr_b32 s13, s13, 29
	s_add_i32 s13, s74, s13
	s_ashr_i32 s14, s13, 3
	s_and_b32 s13, s13, -8
	s_sub_i32 s13, s74, s13
	s_add_i32 s13, s13, s14
	s_ashr_i32 s14, s13, 31
	s_lshr_b32 s14, s14, 28
	s_add_i32 s14, s13, s14
	s_ashr_i32 s14, s14, 4
	s_lshl_b32 s16, s14, 3
	s_sub_i32 s15, 1, s16
	s_lshl_b32 s14, s14, 4
	s_min_u32 s17, s15, 8
	s_sub_i32 s13, s13, s14
	s_sext_i32_i8 s14, s13
	s_waitcnt vmcnt(4)
	v_cvt_f32_ubyte0_e32 v2, s17
	v_cvt_f32_i32_e32 v1, s14
	v_rcp_iflag_f32_e32 v3, v2
	s_ashr_i32 s14, s14, 30
	s_or_b32 s18, s14, 1
	v_mul_f32_e32 v3, v1, v3
	v_trunc_f32_e32 v3, v3
	v_fma_f32 v1, -v3, v2, v1
	v_cvt_i32_f32_e32 v3, v3
	v_cmp_ge_f32_e64 s[14:15], |v1|, v2
	s_and_b64 s[14:15], s[14:15], exec
	s_cselect_b32 s14, s18, 0
	v_readfirstlane_b32 s15, v3
	s_add_i32 s14, s15, s14
	s_sext_i32_i8 s68, s14
	s_mul_i32 s14, s14, s17
	s_sub_i32 s13, s13, s14
	s_sext_i32_i8 s13, s13
	s_add_i32 s58, s16, s13

;     __device__ __forceinline__ bool operator()(f32x4 (&acc)[2][2][4][2], const Unit& u, int wr, int wc, int fr, int fq) const {
;     ...
;                     *(u32x4*)(O + (size_t)row * ldc + col0) = w; }
; __global__ void __launch_bounds__(NTHREADS, 2) mega_fwd(Args a) {
;     ...
;         pg8::Gemm g{XB, (const bf16_t*)(ws + WS_W13_1), D, D, D, S, 2 * FF}; pg8::StaticOrder so; so.init(S, 2 * FF, G, (int)blockIdx.x);
;         pg8::Epi E{}; E.mode = pg8::M_SWIGLU; E.ssq = ssq0; E.O = U; E.ldc = FF;
;         pg8::gemm_phase(lds, g, so, E);
.LBB0_299:
	s_and_b32 s22, s15, 3
	s_lshl_b32 s53, s14, 6
	s_lshl_b32 s23, s14, 13
	s_lshl_b32 s54, s22, 5
	s_add_u32 s14, s28, 0x10000
	s_mov_b64 s[16:17], 0x80
	s_addc_u32 s15, s29, 0
	s_add_i32 m0, s39, 0x18000
	v_lshl_add_u64 v[8:9], v[8:9], 0, s[16:17]
	s_waitcnt vmcnt(2)
	s_barrier
	global_load_lds_dwordx4 v[8:9], off
	v_lshl_add_u64 v[6:7], v[6:7], 0, s[16:17]
	s_add_i32 m0, s39, 0x1a000
	s_add_i32 s55, s39, 0x8000
	s_add_i32 s56, s39, 0xa000
	global_load_lds_dwordx4 v[6:7], off
	v_lshl_add_u64 v[2:3], v[2:3], 0, s[16:17]
	s_mov_b32 m0, s55
	s_add_u32 s18, s40, 0x40080
	global_load_lds_dwordx4 v[2:3], off
	v_lshl_add_u64 v[2:3], v[4:5], 0, s[16:17]
	s_mov_b32 m0, s56
	s_addc_u32 s19, s41, 0
	global_load_lds_dwordx4 v[2:3], off
	s_add_i32 m0, s39, 0x1c000
	v_lshl_add_u64 v[2:3], s[18:19], 0, v[148:149]
	global_load_lds_dwordx4 v[2:3], off
	v_lshl_add_u64 v[2:3], s[18:19], 0, v[152:153]
	s_add_i32 m0, s39, 0x1e000
	s_sext_i32_i16 s62, s2
	global_load_lds_dwordx4 v[2:3], off
	s_waitcnt vmcnt(6)
	v_lshlrev_b32_e32 v2, 6, v163
	s_movk_i32 s2, 0x3c0
	v_lshlrev_b32_e32 v3, 2, v163
	v_and_or_b32 v2, v2, s2, v165
	v_and_b32_e32 v3, 32, v3
	v_lshl_or_b32 v136, s22, 12, v166
	v_bitop3_b32 v2, v2, s23, v3 bitop3:0xde
	s_barrier
	s_ashr_i32 s57, s11, 31
	s_cmpk_lt_u32 s3, 0x100
	s_cselect_b64 s[18:19], -1, 0
	s_add_i32 s58, 0, 0x10000
	s_add_i32 s59, 0, 0x14000
	v_mov_b64_e32 v[130:131], 0x580
	v_mov_b64_e32 v[132:133], 0x57f
	v_add_u32_e32 v137, s58, v136
	v_add_u32_e32 v138, s59, v136
	v_add_u32_e32 v139, 0, v2
	v_mov_b32_e32 v140, 0x358637bd
	s_movk_i32 s68, 0x2000
	s_branch .LBB0_302

; #define PG8_STAGE(bufoff, gbase, voff) do { _Pragma("unroll") for (int _i = 0; _i < 2; ++_i) \
;         __builtin_amdgcn_global_load_lds((const unsigned*)((const char*)(gbase) + (voff)[_i]), (LAS unsigned*)(lds + (bufoff) + ldsw + _i * 8192), 16, 0, 0); } while (0)
; #define PG8_WAIT_V(n) asm volatile("s_waitcnt vmcnt(" #n ")" ::: "memory")
; #define PG8_BAR __builtin_amdgcn_s_barrier()
; __device__ __forceinline__ void gemm_phase(LAS unsigned char* lds, const Gemm g, const StaticOrder S, const Epi E) {
;     ...
;     unsigned voffA[2], voffB[2];
; #pragma unroll
;     for (int i = 0; i < 2; ++i) { int R, C; stage_rc(tid * 16 + i * 8192, R, C); const int Rb = (R & ~31) + perm32(R & 31);
;         voffA[i] = (unsigned)(R * g.lda + C) * 2u; voffB[i] = (unsigned)(Rb * g.ldb + C) * 2u; }
;     const size_t kstep = (size_t)(BK * 2);
;     const size_t hstepA = (size_t)HALF * g.lda * 2, hstepB = (size_t)HALF * g.ldb * 2;
;     const size_t tstepA = 2 * hstepA, tstepB = 2 * hstepB;
;     const unsigned ldsw = (unsigned)wid * 1024u;
;     const int aoff = lds_byte(wr * 64 + fr, fq * 8), boff = lds_byte(wc * 32 + fr, fq * 8);
;     ...
;     Unit cur, nxt; int ui = 0;
;     if (!S.next(0, cur)) return;
;     cur.seg = 0;
;     const char* cA = gA + (size_t)cur.pm * tstepA + (cur.half == 2 ? hstepA : 0); const char* cB = gB + (size_t)cur.pn * tstepB;
;     PG8_STAGE(PG8_SB(0, 0), cB, voffB); PG8_STAGE(PG8_SB(0, 1), cB + hstepB, voffB); PG8_STAGE(PG8_SA(0, 0), cA, voffA); PG8_STAGE(PG8_SA(0, 1), cA + hstepA, voffA);
;     if (wr == 1) PG8_BAR;
;     PG8_WAIT_V(2); PG8_BAR;
;     PG8_STAGE(PG8_SB(1, 0), cB + kstep, voffB); PG8_STAGE(PG8_SA(1, 0), cA + kstep, voffA); PG8_STAGE(PG8_SB(1, 1), cB + hstepB + kstep, voffB);
;     PG8_WAIT_V(6); PG8_BAR;
.LBB0_466:
	s_waitcnt vmcnt(0) lgkmcnt(0)
	v_lshrrev_b32_e32 v4, 1, v198
	v_lshrrev_b32_e32 v5, 5, v198
	v_and_b32_e32 v4, 24, v4
	v_and_b32_e32 v5, 4, v5
	v_bfe_u32 v6, v198, 2, 2
	v_lshlrev_b32_e32 v1, 4, v198
	v_and_b32_e32 v2, 32, v198
	v_bfe_u32 v3, v198, 2, 4
	v_or3_b32 v4, v5, v6, v4
	v_lshrrev_b32_e32 v5, 3, v198
	s_movk_i32 s3, 0x70
	v_bitop3_b32 v10, v1, v2, 48 bitop3:0x6c
	v_and_or_b32 v6, v5, s3, v3
	s_movk_i32 s3, 0x60
	v_add_u32_e32 v1, 0x2000, v1
	v_and_or_b32 v5, v5, s3, v4
	v_lshrrev_b32_e32 v1, 7, v1
	s_movk_i32 s3, 0xf0
	s_lshr_b32 s2, s24, 6
	v_and_b32_e32 v11, 64, v198
	v_and_or_b32 v3, v1, s3, v3
	s_movk_i32 s3, 0xe0
	v_or_b32_e32 v2, v10, v11
	v_and_or_b32 v1, v1, s3, v4
	s_lshr_b32 s3, s24, 8
	s_lshl_b32 s42, s2, 10
	s_mul_i32 s17, s59, 0x160000
	v_lshrrev_b32_e32 v2, 1, v2
	v_mul_u32_u24_e32 v5, 0xb00, v5
	s_mul_hi_i32 s16, s59, 0x160000
	s_add_u32 s38, s6, s17
	v_or_b32_e32 v5, v5, v2
	s_addc_u32 s39, s7, s16
	s_add_i32 s43, s42, 0
	v_lshlrev_b32_e32 v156, 1, v5
	s_add_i32 m0, s43, 0x10000
	s_mul_i32 s5, s62, 0x200000
	global_load_lds_dwordx4 v156, s[38:39]
	s_add_i32 m0, s43, 0x12000
	v_mul_u32_u24_e32 v1, 0xb00, v1
	s_mul_hi_i32 s4, s62, 0x200000
	s_add_u32 s40, s14, s5
	v_or_b32_e32 v1, v1, v2
	s_addc_u32 s41, s15, s4
	v_lshlrev_b32_e32 v160, 1, v1
	s_add_u32 s4, s38, 0xb0000
	v_mul_u32_u24_e32 v12, 0x1000, v6
	global_load_lds_dwordx4 v160, s[38:39]
	s_addc_u32 s5, s39, 0
	s_add_i32 m0, s43, 0x14000
	v_or_b32_e32 v6, v2, v12
	v_mul_u32_u24_e32 v13, 0x1000, v3
	global_load_lds_dwordx4 v156, s[4:5]
	s_add_i32 m0, s43, 0x16000
	s_add_i32 s44, s43, 0x2000
	v_lshlrev_b32_e32 v154, 1, v6
	v_or_b32_e32 v3, v13, v2
	global_load_lds_dwordx4 v160, s[4:5]
	s_mov_b32 m0, s43
	s_add_u32 s4, s40, 0x100000
	v_lshlrev_b32_e32 v158, 1, v3
	global_load_lds_dwordx4 v154, s[40:41]
	s_mov_b32 m0, s44
	s_addc_u32 s5, s41, 0
	s_add_i32 s45, s43, 0x4000
	global_load_lds_dwordx4 v158, s[40:41]
	s_mov_b32 m0, s45
	s_add_i32 s46, s43, 0x6000
	global_load_lds_dwordx4 v154, s[4:5]
	s_mov_b32 m0, s46
	v_mov_b32_e32 v157, 0
	global_load_lds_dwordx4 v158, s[4:5]
	v_mov_b32_e32 v161, v157
	v_mov_b32_e32 v155, v157
	v_mov_b32_e32 v159, v157
	s_cmp_eq_u32 s3, 1
	s_mov_b32 s17, 0
	v_lshl_add_u64 v[8:9], s[38:39], 0, v[156:157]
	v_lshl_add_u64 v[6:7], s[38:39], 0, v[160:161]
	v_lshl_add_u64 v[2:3], s[40:41], 0, v[154:155]
	s_cselect_b64 s[18:19], -1, 0
	s_cmp_lg_u32 s3, 1
	v_lshl_add_u64 v[4:5], s[40:41], 0, v[158:159]
	s_cbranch_scc1 .LBB0_468
	s_barrier

; __device__ __forceinline__ void gemm_phase(LAS unsigned char* lds, const Gemm g, const StaticOrder S, const Epi E) {
;     ...
;         if (cur.seg + 1 < nsegs) { nxt = cur; nxt.seg = cur.seg + 1; has_next = true; } else { has_next = S.next(ui + 1, nxt); nxt.seg = 0; }
;         const char* nA = has_next ? PG8_SEGA(nxt.seg) + (size_t)nxt.pm * tstepA + (nxt.half == 2 ? hstepA : 0) : cA; const char* nB = has_next ? PG8_SEGB(nxt.seg) + (size_t)nxt.pn * tstepB : cB;
.LBB0_477:
	s_nop 0
	v_cndmask_b32_e64 v2, 0, 1, s[4:5]
	v_cmp_ne_u32_e64 s[2:3], 1, v2
	s_andn2_b64 vcc, exec, s[4:5]
	s_mov_b64 s[26:27], s[40:41]
	s_cbranch_vccnz .LBB0_479
	s_mul_i32 s5, s58, 0x200000
	s_mul_hi_i32 s4, s58, 0x200000
	s_add_u32 s26, s14, s5
	s_addc_u32 s27, s15, s4

; #define PG8_STAGE(bufoff, gbase, voff) do { _Pragma("unroll") for (int _i = 0; _i < 2; ++_i) \
;         __builtin_amdgcn_global_load_lds((const unsigned*)((const char*)(gbase) + (voff)[_i]), (LAS unsigned*)(lds + (bufoff) + ldsw + _i * 8192), 16, 0, 0); } while (0)
; #define PG8_LDA(dst, b, h) do { _Pragma("unroll") for (int m = 0; m < 4; ++m) _Pragma("unroll") for (int k = 0; k < 2; ++k) dst[m][k] = *(const LAS bf16x8*)(lds + PG8_SA(b, h) + aoff + m * 2048 + k * 1024); } while (0)
; #define PG8_LDB(dst, b, h) do { _Pragma("unroll") for (int n = 0; n < 2; ++n) _Pragma("unroll") for (int k = 0; k < 2; ++k) dst[n][k] = *(const LAS bf16x8*)(lds + PG8_SB(b, h) + boff + n * 2048 + k * 1024); } while (0)
; #define PG8_MMA(ai, bj, At, Bt) do { __builtin_amdgcn_s_setprio(1); _Pragma("unroll") for (int m = 0; m < 4; ++m) _Pragma("unroll") for (int n = 0; n < 2; ++n) _Pragma("unroll") for (int k = 0; k < 2; ++k) \
;         acc[ai][bj][m][n] = __builtin_amdgcn_mfma_f32_16x16x32_bf16(Bt[n][k], At[m][k], acc[ai][bj][m][n], 0, 0, 0); __builtin_amdgcn_s_setprio(0); } while (0)
; #define PG8_BAR __builtin_amdgcn_s_barrier()
; __device__ __forceinline__ void gemm_phase(LAS unsigned char* lds, const Gemm g, const StaticOrder S, const Epi E) {
;     ...
;         for (int t = 0; t < nt; t += 2) {
;             const bool last = (t == nt - 2);
;             const char* a1 = cA + (size_t)(t + 1) * kstep;
;             const char* a2 = last ? nA : cA + (size_t)(t + 2) * kstep; const char* b2 = last ? nB : cB + (size_t)(t + 2) * kstep;
;             const char* a3 = a2 + kstep; const char* b3 = b2 + kstep;
;             PG8_LDB(B0, 0, 0); PG8_LDB(B1, 0, 1); PG8_SCHED; PG8_LDA(At, 0, 0); PG8_STAGE(PG8_SA(1, 1), a1 + hstepA, voffA);
;             PG8_WAIT_V(8); PG8_WAIT_L(0); PG8_BAR; PG8_MMA(0, 0, At, B0); PG8_MMA(0, 1, At, B1); PG8_BAR; PG8_SCHED;
;             if (full) PG8_LDA(At, 0, 1); PG8_STAGE(PG8_SB(0, 0), b2, voffB); PG8_STAGE(PG8_SB(0, 1), b2 + hstepB, voffB); PG8_STAGE(PG8_SA(0, 0), a2, voffA);
;             PG8_WAIT_V(8); PG8_WAIT_L(0); PG8_BAR; if (full) { PG8_MMA(1, 0, At, B0); PG8_MMA(1, 1, At, B1); } PG8_BAR; PG8_SCHED;
;             PG8_LDB(B0, 1, 0); PG8_LDB(B1, 1, 1); PG8_SCHED; PG8_LDA(At, 1, 0); PG8_STAGE(PG8_SA(0, 1), a2 + hstepA, voffA);
;             PG8_WAIT_V(8); PG8_WAIT_L(0); PG8_BAR; PG8_MMA(0, 0, At, B0); PG8_MMA(0, 1, At, B1); PG8_BAR; PG8_SCHED;
.LBB0_481:
	s_add_u32 s63, s38, 0x100
	s_addc_u32 s64, s39, 0
	s_add_u32 s4, s40, 0x100080
	v_mov_b32_e32 v2, 0
	s_addc_u32 s5, s41, 0
	s_mov_b32 s65, -2
	s_waitcnt lgkmcnt(0)
	v_mov_b32_e32 v3, v2
	v_mov_b32_e32 v4, v2
	v_mov_b32_e32 v5, v2
	v_mov_b32_e32 v6, v2
	v_mov_b32_e32 v7, v2
	v_mov_b32_e32 v8, v2
	v_mov_b32_e32 v9, v2
	v_mov_b32_e32 v18, v2
	v_mov_b32_e32 v19, v2
	v_mov_b32_e32 v20, v2
	v_mov_b32_e32 v21, v2
	v_mov_b32_e32 v22, v2
	v_mov_b32_e32 v23, v2
	v_mov_b32_e32 v24, v2
	v_mov_b32_e32 v25, v2
	v_mov_b32_e32 v34, v2
	v_mov_b32_e32 v35, v2
	v_mov_b32_e32 v36, v2
	v_mov_b32_e32 v37, v2
	v_mov_b32_e32 v38, v2
	v_mov_b32_e32 v39, v2
	v_mov_b32_e32 v40, v2
	v_mov_b32_e32 v41, v2
	v_mov_b32_e32 v50, v2
	v_mov_b32_e32 v51, v2
	v_mov_b32_e32 v52, v2
	v_mov_b32_e32 v53, v2
	v_mov_b32_e32 v54, v2
	v_mov_b32_e32 v55, v2
	v_mov_b32_e32 v56, v2
	v_mov_b32_e32 v57, v2
	v_mov_b32_e32 v10, v2
	v_mov_b32_e32 v11, v2
	v_mov_b32_e32 v12, v2
	v_mov_b32_e32 v13, v2
	v_mov_b32_e32 v14, v2
	v_mov_b32_e32 v15, v2
	v_mov_b32_e32 v16, v2
	v_mov_b32_e32 v17, v2
	v_mov_b32_e32 v26, v2
	v_mov_b32_e32 v27, v2
	v_mov_b32_e32 v28, v2
	v_mov_b32_e32 v29, v2
	v_mov_b32_e32 v30, v2
	v_mov_b32_e32 v31, v2
	v_mov_b32_e32 v32, v2
	v_mov_b32_e32 v33, v2
	v_mov_b32_e32 v42, v2
	v_mov_b32_e32 v43, v2
	v_mov_b32_e32 v44, v2
	v_mov_b32_e32 v45, v2
	v_mov_b32_e32 v46, v2
	v_mov_b32_e32 v47, v2
	v_mov_b32_e32 v48, v2
	v_mov_b32_e32 v49, v2
	v_mov_b32_e32 v58, v2
	v_mov_b32_e32 v59, v2
	v_mov_b32_e32 v60, v2
	v_mov_b32_e32 v61, v2
	v_mov_b32_e32 v62, v2
	v_mov_b32_e32 v63, v2
	v_mov_b32_e32 v64, v2
	v_mov_b32_e32 v65, v2
	v_mov_b32_e32 v66, v2
	v_mov_b32_e32 v67, v2
	v_mov_b32_e32 v68, v2
	v_mov_b32_e32 v69, v2
	v_mov_b32_e32 v70, v2
	v_mov_b32_e32 v71, v2
	v_mov_b32_e32 v72, v2
	v_mov_b32_e32 v73, v2
	v_mov_b32_e32 v82, v2
	v_mov_b32_e32 v83, v2
	v_mov_b32_e32 v84, v2
	v_mov_b32_e32 v85, v2
	v_mov_b32_e32 v86, v2
	v_mov_b32_e32 v87, v2
	v_mov_b32_e32 v88, v2
	v_mov_b32_e32 v89, v2
	v_mov_b32_e32 v98, v2
	v_mov_b32_e32 v99, v2
	v_mov_b32_e32 v100, v2
	v_mov_b32_e32 v101, v2
	v_mov_b32_e32 v102, v2
	v_mov_b32_e32 v103, v2
	v_mov_b32_e32 v104, v2
	v_mov_b32_e32 v105, v2
	v_mov_b32_e32 v114, v2
	v_mov_b32_e32 v115, v2
	v_mov_b32_e32 v116, v2
	v_mov_b32_e32 v117, v2
	v_mov_b32_e32 v118, v2
	v_mov_b32_e32 v119, v2
	v_mov_b32_e32 v120, v2
	v_mov_b32_e32 v121, v2
	v_mov_b32_e32 v74, v2
	v_mov_b32_e32 v75, v2
	v_mov_b32_e32 v76, v2
	v_mov_b32_e32 v77, v2
	v_mov_b32_e32 v78, v2
	v_mov_b32_e32 v79, v2
	v_mov_b32_e32 v80, v2
	v_mov_b32_e32 v81, v2
	v_mov_b32_e32 v90, v2
	v_mov_b32_e32 v91, v2
	v_mov_b32_e32 v92, v2
	v_mov_b32_e32 v93, v2
	v_mov_b32_e32 v94, v2
	v_mov_b32_e32 v95, v2
	v_mov_b32_e32 v96, v2
	v_mov_b32_e32 v97, v2
	v_mov_b32_e32 v106, v2
	v_mov_b32_e32 v107, v2
	v_mov_b32_e32 v108, v2
	v_mov_b32_e32 v109, v2
	v_mov_b32_e32 v110, v2
	v_mov_b32_e32 v111, v2
	v_mov_b32_e32 v112, v2
	v_mov_b32_e32 v113, v2
	v_mov_b32_e32 v122, v2
	v_mov_b32_e32 v123, v2
	v_mov_b32_e32 v124, v2
	v_mov_b32_e32 v125, v2
	v_mov_b32_e32 v126, v2
	v_mov_b32_e32 v127, v2
	v_mov_b32_e32 v128, v2
	v_mov_b32_e32 v129, v2
.LBB0_482:
	ds_read_b128 v[130:133], v190
	ds_read_b128 v[134:137], v190 offset:1024
	ds_read_b128 v[138:141], v190 offset:2048
	ds_read_b128 v[142:145], v190 offset:3072
	ds_read_b128 v[146:149], v191
	ds_read_b128 v[150:153], v191 offset:1024
	ds_read_b128 v[170:173], v191 offset:2048
	ds_read_b128 v[174:177], v191 offset:3072
	s_add_u32 s38, s4, 0xfff00080
	s_addc_u32 s39, s5, -1
	s_cmp_eq_u32 s65, 40
	s_cselect_b32 s41, s27, s39
	s_cselect_b32 s40, s26, s38
	s_cselect_b32 s39, s37, s64
	s_cselect_b32 s38, s36, s63
	v_lshl_add_u64 v[186:187], s[4:5], 0, v[164:165]
	s_add_i32 m0, s43, 0xc000
	ds_read_b128 v[178:181], v192
	ds_read_b128 v[182:185], v192 offset:1024
	ds_read_b128 v[194:197], v192 offset:2048
	ds_read_b128 v[200:203], v192 offset:3072
	ds_read_b128 v[204:207], v192 offset:4096
	ds_read_b128 v[208:211], v192 offset:5120
	ds_read_b128 v[212:215], v192 offset:6144
	ds_read_b128 v[216:219], v192 offset:7168
	global_load_lds_dwordx4 v[186:187], off
	v_lshl_add_u64 v[186:187], s[4:5], 0, v[162:163]
	s_add_i32 m0, s43, 0xe000
	s_nop 0
	global_load_lds_dwordx4 v[186:187], off
	s_waitcnt vmcnt(8)
	s_waitcnt lgkmcnt(0)
	s_barrier
	s_setprio 1
	s_waitcnt lgkmcnt(0)
	v_mfma_f32_16x16x32_bf16 v[126:129], v[130:133], v[178:181], v[126:129]
	v_mfma_f32_16x16x32_bf16 v[122:125], v[138:141], v[178:181], v[122:125]
	v_mfma_f32_16x16x32_bf16 v[110:113], v[130:133], v[194:197], v[110:113]
	v_mfma_f32_16x16x32_bf16 v[106:109], v[138:141], v[194:197], v[106:109]
	v_mfma_f32_16x16x32_bf16 v[94:97], v[130:133], v[204:207], v[94:97]
	v_mfma_f32_16x16x32_bf16 v[90:93], v[138:141], v[204:207], v[90:93]
	v_mfma_f32_16x16x32_bf16 v[78:81], v[130:133], v[212:215], v[78:81]
	v_mfma_f32_16x16x32_bf16 v[74:77], v[138:141], v[212:215], v[74:77]
	v_mfma_f32_16x16x32_bf16 v[126:129], v[134:137], v[182:185], v[126:129]
	v_mfma_f32_16x16x32_bf16 v[122:125], v[142:145], v[182:185], v[122:125]
	v_mfma_f32_16x16x32_bf16 v[110:113], v[134:137], v[200:203], v[110:113]
	v_mfma_f32_16x16x32_bf16 v[106:109], v[142:145], v[200:203], v[106:109]
	v_mfma_f32_16x16x32_bf16 v[94:97], v[134:137], v[208:211], v[94:97]
	v_mfma_f32_16x16x32_bf16 v[90:93], v[142:145], v[208:211], v[90:93]
	v_mfma_f32_16x16x32_bf16 v[78:81], v[134:137], v[216:219], v[78:81]
	v_mfma_f32_16x16x32_bf16 v[74:77], v[142:145], v[216:219], v[74:77]
	s_setprio 0
	s_setprio 1
	v_mfma_f32_16x16x32_bf16 v[118:121], v[146:149], v[178:181], v[118:121]
	v_mfma_f32_16x16x32_bf16 v[114:117], v[170:173], v[178:181], v[114:117]
	v_mfma_f32_16x16x32_bf16 v[102:105], v[146:149], v[194:197], v[102:105]
	v_mfma_f32_16x16x32_bf16 v[98:101], v[170:173], v[194:197], v[98:101]
	v_mfma_f32_16x16x32_bf16 v[86:89], v[146:149], v[204:207], v[86:89]
	v_mfma_f32_16x16x32_bf16 v[82:85], v[170:173], v[204:207], v[82:85]
	v_mfma_f32_16x16x32_bf16 v[70:73], v[146:149], v[212:215], v[70:73]
	v_mfma_f32_16x16x32_bf16 v[66:69], v[170:173], v[212:215], v[66:69]
	v_mfma_f32_16x16x32_bf16 v[118:121], v[150:153], v[182:185], v[118:121]
	v_mfma_f32_16x16x32_bf16 v[114:117], v[174:177], v[182:185], v[114:117]
	v_mfma_f32_16x16x32_bf16 v[102:105], v[150:153], v[200:203], v[102:105]
	v_mfma_f32_16x16x32_bf16 v[98:101], v[174:177], v[200:203], v[98:101]
	v_mfma_f32_16x16x32_bf16 v[86:89], v[150:153], v[208:211], v[86:89]
	v_mfma_f32_16x16x32_bf16 v[82:85], v[174:177], v[208:211], v[82:85]
	v_mfma_f32_16x16x32_bf16 v[70:73], v[150:153], v[216:219], v[70:73]
	v_mfma_f32_16x16x32_bf16 v[66:69], v[174:177], v[216:219], v[66:69]
	s_setprio 0
	s_barrier
; #define PG8_STAGE(bufoff, gbase, voff) do { _Pragma("unroll") for (int _i = 0; _i < 2; ++_i) \
;         __builtin_amdgcn_global_load_lds((const unsigned*)((const char*)(gbase) + (voff)[_i]), (LAS unsigned*)(lds + (bufoff) + ldsw + _i * 8192), 16, 0, 0); } while (0)
; #define PG8_LDA(dst, b, h) do { _Pragma("unroll") for (int m = 0; m < 4; ++m) _Pragma("unroll") for (int k = 0; k < 2; ++k) dst[m][k] = *(const LAS bf16x8*)(lds + PG8_SA(b, h) + aoff + m * 2048 + k * 1024); } while (0)
; #define PG8_LDB(dst, b, h) do { _Pragma("unroll") for (int n = 0; n < 2; ++n) _Pragma("unroll") for (int k = 0; k < 2; ++k) dst[n][k] = *(const LAS bf16x8*)(lds + PG8_SB(b, h) + boff + n * 2048 + k * 1024); } while (0)
; #define PG8_MMA(ai, bj, At, Bt) do { __builtin_amdgcn_s_setprio(1); _Pragma("unroll") for (int m = 0; m < 4; ++m) _Pragma("unroll") for (int n = 0; n < 2; ++n) _Pragma("unroll") for (int k = 0; k < 2; ++k) \
;         acc[ai][bj][m][n] = __builtin_amdgcn_mfma_f32_16x16x32_bf16(Bt[n][k], At[m][k], acc[ai][bj][m][n], 0, 0, 0); __builtin_amdgcn_s_setprio(0); } while (0)
; #define PG8_WAIT_V(n) asm volatile("s_waitcnt vmcnt(" #n ")" ::: "memory")
; #define PG8_WAIT_L(n) asm volatile("s_waitcnt lgkmcnt(" #n ")" ::: "memory")
; #define PG8_BAR __builtin_amdgcn_s_barrier()
; #define PG8_SCHED __builtin_amdgcn_sched_barrier(0)
; __device__ __forceinline__ void gemm_phase(LAS unsigned char* lds, const Gemm g, const StaticOrder S, const Epi E) {
;     ...
;             if (full) PG8_LDA(At, 0, 1); PG8_STAGE(PG8_SB(0, 0), b2, voffB); PG8_STAGE(PG8_SB(0, 1), b2 + hstepB, voffB); PG8_STAGE(PG8_SA(0, 0), a2, voffA);
;             PG8_WAIT_V(8); PG8_WAIT_L(0); PG8_BAR; if (full) { PG8_MMA(1, 0, At, B0); PG8_MMA(1, 1, At, B1); } PG8_BAR; PG8_SCHED;
;             PG8_LDB(B0, 1, 0); PG8_LDB(B1, 1, 1); PG8_SCHED; PG8_LDA(At, 1, 0); PG8_STAGE(PG8_SA(0, 1), a2 + hstepA, voffA);
;             PG8_WAIT_V(8); PG8_WAIT_L(0); PG8_BAR; PG8_MMA(0, 0, At, B0); PG8_MMA(0, 1, At, B1); PG8_BAR; PG8_SCHED;
;             if (full) PG8_LDA(At, 1, 1); PG8_STAGE(PG8_SB(1, 0), b3, voffB); PG8_STAGE(PG8_SB(1, 1), b3 + hstepB, voffB); PG8_STAGE(PG8_SA(1, 0), a3, voffA);
	s_add_i32 s66, s54, s42
	v_lshl_add_u64 v[186:187], s[38:39], 0, v[156:157]
	s_mov_b32 m0, s66
	ds_read_b128 v[178:181], v192 offset:16384
	ds_read_b128 v[182:185], v192 offset:17408
	ds_read_b128 v[194:197], v192 offset:18432
	ds_read_b128 v[200:203], v192 offset:19456
	ds_read_b128 v[204:207], v192 offset:20480
	ds_read_b128 v[208:211], v192 offset:21504
	ds_read_b128 v[212:215], v192 offset:22528
	ds_read_b128 v[216:219], v192 offset:23552
	global_load_lds_dwordx4 v[186:187], off
	s_add_i32 m0, s66, 0x2000
	s_add_u32 s66, s38, 0xb0000
	v_lshl_add_u64 v[220:221], s[38:39], 0, v[160:161]
	s_addc_u32 s67, s39, 0
	s_add_i32 s68, s55, s42
	global_load_lds_dwordx4 v[220:221], off
	v_lshl_add_u64 v[222:223], s[66:67], 0, v[156:157]
	s_mov_b32 m0, s68
	v_lshl_add_u64 v[224:225], s[40:41], 0, v[158:159]
	global_load_lds_dwordx4 v[222:223], off
	v_lshl_add_u64 v[222:223], s[66:67], 0, v[160:161]
	s_add_i32 m0, s68, 0x2000
	s_nop 0
	global_load_lds_dwordx4 v[222:223], off
	v_lshl_add_u64 v[222:223], s[40:41], 0, v[154:155]
	s_mov_b32 m0, s43
	s_nop 0
	global_load_lds_dwordx4 v[222:223], off
	s_mov_b32 m0, s44
	s_nop 0
	global_load_lds_dwordx4 v[224:225], off
	s_waitcnt vmcnt(8)
	s_waitcnt lgkmcnt(0)
	s_barrier
	s_setprio 1
	s_waitcnt lgkmcnt(0)
	v_mfma_f32_16x16x32_bf16 v[62:65], v[130:133], v[178:181], v[62:65]
	v_mfma_f32_16x16x32_bf16 v[58:61], v[138:141], v[178:181], v[58:61]
	v_mfma_f32_16x16x32_bf16 v[46:49], v[130:133], v[194:197], v[46:49]
	v_mfma_f32_16x16x32_bf16 v[42:45], v[138:141], v[194:197], v[42:45]
	v_mfma_f32_16x16x32_bf16 v[30:33], v[130:133], v[204:207], v[30:33]
	v_mfma_f32_16x16x32_bf16 v[26:29], v[138:141], v[204:207], v[26:29]
	v_mfma_f32_16x16x32_bf16 v[14:17], v[130:133], v[212:215], v[14:17]
	v_mfma_f32_16x16x32_bf16 v[10:13], v[138:141], v[212:215], v[10:13]
	v_mfma_f32_16x16x32_bf16 v[62:65], v[134:137], v[182:185], v[62:65]
	v_mfma_f32_16x16x32_bf16 v[58:61], v[142:145], v[182:185], v[58:61]
	v_mfma_f32_16x16x32_bf16 v[46:49], v[134:137], v[200:203], v[46:49]
	v_mfma_f32_16x16x32_bf16 v[42:45], v[142:145], v[200:203], v[42:45]
	v_mfma_f32_16x16x32_bf16 v[30:33], v[134:137], v[208:211], v[30:33]
	v_mfma_f32_16x16x32_bf16 v[26:29], v[142:145], v[208:211], v[26:29]
	v_mfma_f32_16x16x32_bf16 v[14:17], v[134:137], v[216:219], v[14:17]
	v_mfma_f32_16x16x32_bf16 v[10:13], v[142:145], v[216:219], v[10:13]
	s_setprio 0
	s_setprio 1
	v_mfma_f32_16x16x32_bf16 v[54:57], v[146:149], v[178:181], v[54:57]
	v_mfma_f32_16x16x32_bf16 v[50:53], v[170:173], v[178:181], v[50:53]
	v_mfma_f32_16x16x32_bf16 v[38:41], v[146:149], v[194:197], v[38:41]
	v_mfma_f32_16x16x32_bf16 v[34:37], v[170:173], v[194:197], v[34:37]
	v_mfma_f32_16x16x32_bf16 v[22:25], v[146:149], v[204:207], v[22:25]
	v_mfma_f32_16x16x32_bf16 v[18:21], v[170:173], v[204:207], v[18:21]
	v_mfma_f32_16x16x32_bf16 v[6:9], v[146:149], v[212:215], v[6:9]
	v_mfma_f32_16x16x32_bf16 v[2:5], v[170:173], v[212:215], v[2:5]
	v_mfma_f32_16x16x32_bf16 v[54:57], v[150:153], v[182:185], v[54:57]
	v_mfma_f32_16x16x32_bf16 v[50:53], v[174:177], v[182:185], v[50:53]
	v_mfma_f32_16x16x32_bf16 v[38:41], v[150:153], v[200:203], v[38:41]
	v_mfma_f32_16x16x32_bf16 v[34:37], v[174:177], v[200:203], v[34:37]
	v_mfma_f32_16x16x32_bf16 v[22:25], v[150:153], v[208:211], v[22:25]
	v_mfma_f32_16x16x32_bf16 v[18:21], v[174:177], v[208:211], v[18:21]
	v_mfma_f32_16x16x32_bf16 v[6:9], v[150:153], v[216:219], v[6:9]
	v_mfma_f32_16x16x32_bf16 v[2:5], v[174:177], v[216:219], v[2:5]
	s_setprio 0
	s_barrier
	s_add_i32 s66, 0, 0x18000
	s_add_i32 s67, 0, 0x1c000
	v_add_u32_e32 v142, s66, v189
	v_add_u32_e32 v174, s67, v189
	ds_read_b128 v[130:133], v142
	ds_read_b128 v[134:137], v142 offset:1024
	ds_read_b128 v[138:141], v142 offset:2048
	ds_read_b128 v[142:145], v142 offset:3072
	ds_read_b128 v[146:149], v174
	ds_read_b128 v[150:153], v174 offset:1024
	ds_read_b128 v[170:173], v174 offset:2048
	ds_read_b128 v[174:177], v174 offset:3072
	s_add_u32 s40, s40, 0x100000
	s_addc_u32 s41, s41, 0
	s_mov_b32 m0, s45
	v_lshl_add_u64 v[226:227], s[40:41], 0, v[154:155]
	ds_read_b128 v[178:181], v192 offset:32768
	ds_read_b128 v[182:185], v192 offset:33792
	ds_read_b128 v[194:197], v192 offset:34816
	ds_read_b128 v[200:203], v192 offset:35840
	ds_read_b128 v[204:207], v192 offset:36864
	ds_read_b128 v[208:211], v192 offset:37888
	ds_read_b128 v[212:215], v192 offset:38912
	ds_read_b128 v[216:219], v192 offset:39936
	global_load_lds_dwordx4 v[226:227], off
	v_lshl_add_u64 v[226:227], s[40:41], 0, v[158:159]
	s_mov_b32 m0, s46
	s_nop 0
	global_load_lds_dwordx4 v[226:227], off
	s_waitcnt vmcnt(8)
	s_waitcnt lgkmcnt(0)
	s_barrier
; #define PG8_STAGE(bufoff, gbase, voff) do { _Pragma("unroll") for (int _i = 0; _i < 2; ++_i) \
;         __builtin_amdgcn_global_load_lds((const unsigned*)((const char*)(gbase) + (voff)[_i]), (LAS unsigned*)(lds + (bufoff) + ldsw + _i * 8192), 16, 0, 0); } while (0)
; #define PG8_LDA(dst, b, h) do { _Pragma("unroll") for (int m = 0; m < 4; ++m) _Pragma("unroll") for (int k = 0; k < 2; ++k) dst[m][k] = *(const LAS bf16x8*)(lds + PG8_SA(b, h) + aoff + m * 2048 + k * 1024); } while (0)
; #define PG8_LDB(dst, b, h) do { _Pragma("unroll") for (int n = 0; n < 2; ++n) _Pragma("unroll") for (int k = 0; k < 2; ++k) dst[n][k] = *(const LAS bf16x8*)(lds + PG8_SB(b, h) + boff + n * 2048 + k * 1024); } while (0)
; #define PG8_MMA(ai, bj, At, Bt) do { __builtin_amdgcn_s_setprio(1); _Pragma("unroll") for (int m = 0; m < 4; ++m) _Pragma("unroll") for (int n = 0; n < 2; ++n) _Pragma("unroll") for (int k = 0; k < 2; ++k) \
;         acc[ai][bj][m][n] = __builtin_amdgcn_mfma_f32_16x16x32_bf16(Bt[n][k], At[m][k], acc[ai][bj][m][n], 0, 0, 0); __builtin_amdgcn_s_setprio(0); } while (0)
; #define PG8_WAIT_V(n) asm volatile("s_waitcnt vmcnt(" #n ")" ::: "memory")
; #define PG8_WAIT_L(n) asm volatile("s_waitcnt lgkmcnt(" #n ")" ::: "memory")
; #define PG8_BAR __builtin_amdgcn_s_barrier()
; #define PG8_SCHED __builtin_amdgcn_sched_barrier(0)
; __device__ __forceinline__ void gemm_phase(LAS unsigned char* lds, const Gemm g, const StaticOrder S, const Epi E) {
;     ...
;             PG8_LDB(B0, 1, 0); PG8_LDB(B1, 1, 1); PG8_SCHED; PG8_LDA(At, 1, 0); PG8_STAGE(PG8_SA(0, 1), a2 + hstepA, voffA);
;             PG8_WAIT_V(8); PG8_WAIT_L(0); PG8_BAR; PG8_MMA(0, 0, At, B0); PG8_MMA(0, 1, At, B1); PG8_BAR; PG8_SCHED;
;             if (full) PG8_LDA(At, 1, 1); PG8_STAGE(PG8_SB(1, 0), b3, voffB); PG8_STAGE(PG8_SB(1, 1), b3 + hstepB, voffB); PG8_STAGE(PG8_SA(1, 0), a3, voffA);
;             PG8_WAIT_V(8); PG8_WAIT_L(0); PG8_BAR; if (full) { PG8_MMA(1, 0, At, B0); PG8_MMA(1, 1, At, B1); } PG8_BAR; PG8_SCHED;
;         }
	s_setprio 1
	s_waitcnt lgkmcnt(0)
	v_mfma_f32_16x16x32_bf16 v[126:129], v[130:133], v[178:181], v[126:129]
	v_mfma_f32_16x16x32_bf16 v[122:125], v[138:141], v[178:181], v[122:125]
	v_mfma_f32_16x16x32_bf16 v[110:113], v[130:133], v[194:197], v[110:113]
	v_mfma_f32_16x16x32_bf16 v[106:109], v[138:141], v[194:197], v[106:109]
	v_mfma_f32_16x16x32_bf16 v[94:97], v[130:133], v[204:207], v[94:97]
	v_mfma_f32_16x16x32_bf16 v[90:93], v[138:141], v[204:207], v[90:93]
	v_mfma_f32_16x16x32_bf16 v[78:81], v[130:133], v[212:215], v[78:81]
	v_mfma_f32_16x16x32_bf16 v[74:77], v[138:141], v[212:215], v[74:77]
	v_mfma_f32_16x16x32_bf16 v[126:129], v[134:137], v[182:185], v[126:129]
	v_mfma_f32_16x16x32_bf16 v[122:125], v[142:145], v[182:185], v[122:125]
	v_mfma_f32_16x16x32_bf16 v[110:113], v[134:137], v[200:203], v[110:113]
	v_mfma_f32_16x16x32_bf16 v[106:109], v[142:145], v[200:203], v[106:109]
	v_mfma_f32_16x16x32_bf16 v[94:97], v[134:137], v[208:211], v[94:97]
	v_mfma_f32_16x16x32_bf16 v[90:93], v[142:145], v[208:211], v[90:93]
	v_mfma_f32_16x16x32_bf16 v[78:81], v[134:137], v[216:219], v[78:81]
	v_mfma_f32_16x16x32_bf16 v[74:77], v[142:145], v[216:219], v[74:77]
	s_setprio 0
	s_setprio 1
	v_mfma_f32_16x16x32_bf16 v[118:121], v[146:149], v[178:181], v[118:121]
	v_mfma_f32_16x16x32_bf16 v[114:117], v[170:173], v[178:181], v[114:117]
	v_mfma_f32_16x16x32_bf16 v[102:105], v[146:149], v[194:197], v[102:105]
	v_mfma_f32_16x16x32_bf16 v[98:101], v[170:173], v[194:197], v[98:101]
	v_mfma_f32_16x16x32_bf16 v[86:89], v[146:149], v[204:207], v[86:89]
	v_mfma_f32_16x16x32_bf16 v[82:85], v[170:173], v[204:207], v[82:85]
	v_mfma_f32_16x16x32_bf16 v[70:73], v[146:149], v[212:215], v[70:73]
	v_mfma_f32_16x16x32_bf16 v[66:69], v[170:173], v[212:215], v[66:69]
	v_mfma_f32_16x16x32_bf16 v[118:121], v[150:153], v[182:185], v[118:121]
	v_mfma_f32_16x16x32_bf16 v[114:117], v[174:177], v[182:185], v[114:117]
	v_mfma_f32_16x16x32_bf16 v[102:105], v[150:153], v[200:203], v[102:105]
	v_mfma_f32_16x16x32_bf16 v[98:101], v[174:177], v[200:203], v[98:101]
	v_mfma_f32_16x16x32_bf16 v[86:89], v[150:153], v[208:211], v[86:89]
	v_mfma_f32_16x16x32_bf16 v[82:85], v[174:177], v[208:211], v[82:85]
	v_mfma_f32_16x16x32_bf16 v[70:73], v[150:153], v[216:219], v[70:73]
	v_mfma_f32_16x16x32_bf16 v[66:69], v[174:177], v[216:219], v[66:69]
	s_setprio 0
	s_barrier
	s_add_i32 s40, s66, s42
	v_lshl_add_u64 v[186:187], v[186:187], 0, s[22:23]
	s_mov_b32 m0, s40
	ds_read_b128 v[178:181], v192 offset:49152
	ds_read_b128 v[182:185], v192 offset:50176
	ds_read_b128 v[194:197], v192 offset:51200
	ds_read_b128 v[200:203], v192 offset:52224
	ds_read_b128 v[204:207], v192 offset:53248
	ds_read_b128 v[208:211], v192 offset:54272
	ds_read_b128 v[212:215], v192 offset:55296
	ds_read_b128 v[216:219], v192 offset:56320
	global_load_lds_dwordx4 v[186:187], off
	s_add_i32 m0, s40, 0x2000
	s_add_u32 s38, s38, 0xb0080
	v_lshl_add_u64 v[186:187], v[220:221], 0, s[22:23]
	s_addc_u32 s39, s39, 0
	s_add_i32 s40, s67, s42
	global_load_lds_dwordx4 v[186:187], off
	v_lshl_add_u64 v[186:187], s[38:39], 0, v[156:157]
	s_mov_b32 m0, s40
	s_nop 0
	global_load_lds_dwordx4 v[186:187], off
	v_lshl_add_u64 v[186:187], s[38:39], 0, v[160:161]
	s_add_i32 m0, s40, 0x2000
	s_nop 0
	global_load_lds_dwordx4 v[186:187], off
	v_lshl_add_u64 v[186:187], v[222:223], 0, s[22:23]
	s_mov_b32 m0, s48
	s_nop 0
	global_load_lds_dwordx4 v[186:187], off
	v_lshl_add_u64 v[186:187], v[224:225], 0, s[22:23]
	s_mov_b32 m0, s49
	s_nop 0
	global_load_lds_dwordx4 v[186:187], off
	s_waitcnt vmcnt(8)
	s_waitcnt lgkmcnt(0)
	s_barrier
	s_setprio 1
	s_waitcnt lgkmcnt(0)
	v_mfma_f32_16x16x32_bf16 v[62:65], v[130:133], v[178:181], v[62:65]
	v_mfma_f32_16x16x32_bf16 v[58:61], v[138:141], v[178:181], v[58:61]
	v_mfma_f32_16x16x32_bf16 v[46:49], v[130:133], v[194:197], v[46:49]
	v_mfma_f32_16x16x32_bf16 v[42:45], v[138:141], v[194:197], v[42:45]
	v_mfma_f32_16x16x32_bf16 v[30:33], v[130:133], v[204:207], v[30:33]
	v_mfma_f32_16x16x32_bf16 v[26:29], v[138:141], v[204:207], v[26:29]
	v_mfma_f32_16x16x32_bf16 v[14:17], v[130:133], v[212:215], v[14:17]
	v_mfma_f32_16x16x32_bf16 v[10:13], v[138:141], v[212:215], v[10:13]
	v_mfma_f32_16x16x32_bf16 v[62:65], v[134:137], v[182:185], v[62:65]
	v_mfma_f32_16x16x32_bf16 v[58:61], v[142:145], v[182:185], v[58:61]
	v_mfma_f32_16x16x32_bf16 v[46:49], v[134:137], v[200:203], v[46:49]
	v_mfma_f32_16x16x32_bf16 v[42:45], v[142:145], v[200:203], v[42:45]
	v_mfma_f32_16x16x32_bf16 v[30:33], v[134:137], v[208:211], v[30:33]
	v_mfma_f32_16x16x32_bf16 v[26:29], v[142:145], v[208:211], v[26:29]
	v_mfma_f32_16x16x32_bf16 v[14:17], v[134:137], v[216:219], v[14:17]
	v_mfma_f32_16x16x32_bf16 v[10:13], v[142:145], v[216:219], v[10:13]
	s_setprio 0
	s_setprio 1
	v_mfma_f32_16x16x32_bf16 v[54:57], v[146:149], v[178:181], v[54:57]
	v_mfma_f32_16x16x32_bf16 v[50:53], v[170:173], v[178:181], v[50:53]
	v_mfma_f32_16x16x32_bf16 v[38:41], v[146:149], v[194:197], v[38:41]
	v_mfma_f32_16x16x32_bf16 v[34:37], v[170:173], v[194:197], v[34:37]
	v_mfma_f32_16x16x32_bf16 v[22:25], v[146:149], v[204:207], v[22:25]
	v_mfma_f32_16x16x32_bf16 v[18:21], v[170:173], v[204:207], v[18:21]
	v_mfma_f32_16x16x32_bf16 v[6:9], v[146:149], v[212:215], v[6:9]
	v_mfma_f32_16x16x32_bf16 v[2:5], v[170:173], v[212:215], v[2:5]
	v_mfma_f32_16x16x32_bf16 v[54:57], v[150:153], v[182:185], v[54:57]
	v_mfma_f32_16x16x32_bf16 v[50:53], v[174:177], v[182:185], v[50:53]
	v_mfma_f32_16x16x32_bf16 v[38:41], v[150:153], v[200:203], v[38:41]
	v_mfma_f32_16x16x32_bf16 v[34:37], v[174:177], v[200:203], v[34:37]
	v_mfma_f32_16x16x32_bf16 v[22:25], v[150:153], v[208:211], v[22:25]
	v_mfma_f32_16x16x32_bf16 v[18:21], v[174:177], v[208:211], v[18:21]
	v_mfma_f32_16x16x32_bf16 v[6:9], v[150:153], v[216:219], v[6:9]
	v_mfma_f32_16x16x32_bf16 v[2:5], v[174:177], v[216:219], v[2:5]
	s_setprio 0
	s_barrier
	s_add_i32 s65, s65, 2
	s_add_u32 s63, s63, 0x100
	s_addc_u32 s64, s64, 0
	s_add_u32 s4, s4, 0x100
	s_addc_u32 s5, s5, 0
	s_cmp_gt_u32 s65, 41
	s_cbranch_scc0 .LBB0_482
	s_and_b64 vcc, exec, s[24:25]
	s_cbranch_vccz .LBB0_485
	s_barrier

; __device__ __forceinline__ unsigned xb_ld(unsigned* p)              { return __hip_atomic_load(p, __ATOMIC_RELAXED, __HIP_MEMORY_SCOPE_AGENT); }
; __device__ __forceinline__ unsigned xb_add(unsigned* p, unsigned v) { return __hip_atomic_fetch_add(p, v, __ATOMIC_RELAXED, __HIP_MEMORY_SCOPE_AGENT); }
; #define XB_SPIN(cond, bar) do { unsigned _sp = 0; while (cond) { __builtin_amdgcn_s_sleep(1); \
;     if ((++_sp & 255u) == 0u) { if (xb_ld(&(bar)[XB_TMO])) break; if (_sp > XB_SPIN_CAP) { atomicAdd(&(bar)[XB_TMO], 1u); break; } } } } while (0)
; __device__ __forceinline__ void xcd_barrier(const XcdBarrier& b) {
;     ...
;         const unsigned old = xb_add(&bar[XB_XSUB(b.x)], 1u);
;         const unsigned gen = old / nloc;
;         if (old + 1u == (gen + 1u) * nloc) {
;             __builtin_amdgcn_fence(__ATOMIC_RELEASE, "agent");
;             asm volatile("s_waitcnt vmcnt(0)" ::: "memory");
;             const unsigned og = xb_add(&bar[XB_TOP], 1u);
;             const unsigned tg = og / nx;
;             if (og + 1u == (tg + 1u) * nx) xb_add(&bar[XB_TOPGEN], 1u);
;             else XB_SPIN(xb_ld(&bar[XB_TOPGEN]) == tg, bar);
;             __builtin_amdgcn_fence(__ATOMIC_ACQUIRE, "agent");
;             xb_add(&bar[XB_XGEN(b.x)], 1u);
;             asm volatile("s_waitcnt vmcnt(0)" ::: "memory");
;         } else {
.LBB0_536:
	s_andn2_saveexec_b64 s[6:7], s[6:7]
	s_cbranch_execz .LBB0_554
	s_mov_b64 s[6:7], exec
	s_cmp_lg_u32 s98, 0
	s_cbranch_scc1 .Lfast_2
	buffer_inv sc1
	buffer_wbl2 sc1
	s_waitcnt lgkmcnt(0)
	s_waitcnt vmcnt(0)
	v_mbcnt_lo_u32_b32 v2, s6, 0
	v_mbcnt_hi_u32_b32 v2, s7, v2
	v_cmp_eq_u32_e32 vcc, 0, v2
	s_and_saveexec_b64 s[14:15], vcc
	s_cbranch_execz .LBB0_539
	s_bcnt1_i32_b64 s6, s[6:7]
	v_mov_b32_e32 v3, 0x83000
	v_mov_b32_e32 v4, s6
	global_atomic_add v3, v3, v4, s[28:29] offset:1024 sc0

; #define SEAM(k) do { if (IN(k) && IN((k) + 1)) { if (lo < 0) cg::this_grid().sync(); else xcd_barrier(bar); } } while (0)
;     __device__ __forceinline__ bool operator()(f32x4 (&acc)[2][2][4][2], const Unit& u, int wr, int wc, int fr, int fq) const {
;     ...
;                     *(u32x4*)(O + (size_t)row * ldc + col0) = w; }
; __global__ void __launch_bounds__(NTHREADS, 2) mega_fwd(Args a) {
;     ...
;         pg8::Gemm g{XB, (const bf16_t*)(ws + WS_W13_2), D, D, D, S, 2 * FF}; pg8::StaticOrder so; so.init(S, 2 * FF, G, (int)blockIdx.x); so.split = (G == 256) ? 1 : 0;
;         pg8::Epi E{}; E.mode = pg8::M_SWIGLU; E.ssq = ssq2; E.O = U; E.ldc = FF;
;         pg8::gemm_phase(lds, g, so, E); SEAM(7);
.LBB0_1235:
	s_add_i32 s66, s43, 0x18000
	s_mov_b64 s[22:23], 0x80
	s_and_b32 s2, s2, 3
	v_lshl_add_u64 v[10:11], v[10:11], 0, s[22:23]
	s_mov_b32 m0, s66
	s_add_i32 s67, s43, 0x1a000
	s_lshl_b32 s64, s3, 6
	s_lshl_b32 s5, s3, 13
	s_lshl_b32 s65, s2, 5
	s_lshl_b32 s24, s2, 12
	s_waitcnt vmcnt(2)
	s_barrier
	global_load_lds_dwordx4 v[10:11], off
	v_lshl_add_u64 v[8:9], v[8:9], 0, s[22:23]
	s_mov_b32 m0, s67
	s_add_i32 s68, s43, 0x8000
	s_add_i32 s69, s43, 0xa000
	global_load_lds_dwordx4 v[8:9], off
	v_lshl_add_u64 v[4:5], v[4:5], 0, s[22:23]
	s_mov_b32 m0, s68
	s_add_u32 s2, s6, 0x40080
	global_load_lds_dwordx4 v[4:5], off
	v_lshl_add_u64 v[4:5], v[6:7], 0, s[22:23]
	s_mov_b32 m0, s69
	s_addc_u32 s3, s7, 0
	s_add_i32 s70, s43, 0x1c000
	global_load_lds_dwordx4 v[4:5], off
	v_lshl_add_u64 v[4:5], s[2:3], 0, v[202:203]
	s_mov_b32 m0, s70
	s_add_i32 s71, s43, 0x1e000
	global_load_lds_dwordx4 v[4:5], off
	v_lshl_add_u64 v[4:5], s[2:3], 0, v[206:207]
	s_mov_b32 m0, s71
	v_bfe_u32 v199, v198, 4, 2
	global_load_lds_dwordx4 v[4:5], off
	s_waitcnt vmcnt(6)
	v_and_b32_e32 v1, 15, v198
	v_lshlrev_b32_e32 v4, 4, v199
	v_lshlrev_b32_e32 v6, 2, v198
	v_lshlrev_b32_e32 v7, 6, v198
	s_movk_i32 s2, 0x3c0
	v_lshl_or_b32 v5, v1, 6, v4
	v_and_b32_e32 v6, 32, v6
	v_and_or_b32 v4, v7, s2, v4
	v_bitop3_b32 v5, v5, s5, v6 bitop3:0xde
	v_bitop3_b32 v4, s24, v4, v6 bitop3:0xf6
	s_barrier
	s_ashr_i32 s72, s11, 31
	s_cmpk_lt_u32 s4, 0x100
	s_cselect_b64 s[24:25], -1, 0
	s_ashr_i32 s2, s10, 31
	v_lshlrev_b32_e32 v6, 4, v14
	s_lshr_b32 s2, s2, 25
	v_and_b32_e32 v6, 0x78000, v6
	v_lshlrev_b32_e32 v7, 11, v13
	s_add_i32 s2, s10, s2
	v_or3_b32 v6, v3, v6, v7
	s_ashr_i32 s74, s2, 7
	s_and_b32 s2, s2, 0xffffff80
	v_add_u32_e32 v208, v6, v12
	v_lshlrev_b32_e32 v6, 8, v198
	s_sub_i32 s73, s10, s2
	v_and_b32_e32 v6, 0x38000, v6
	v_readlane_b32 s2, v245, 0
	v_or3_b32 v3, v3, v6, v7
	v_readlane_b32 s3, v245, 1
	v_add_u32_e32 v210, v3, v12
	v_add_u32_e32 v220, 0, v4
	v_cndmask_b32_e64 v3, 0, 1, s[2:3]
	s_add_i32 s74, s74, 1
	v_mov_b32_e32 v209, v2
	v_mov_b32_e32 v211, v2
	v_cmp_ne_u32_e64 s[2:3], 1, v3
	s_movk_i32 s62, 0xb1
	v_add_u32_e32 v221, 0x10000, v220
	v_add_u32_e32 v222, 0x14000, v220
	v_add_u32_e32 v223, 0, v5
	v_mov_b32_e32 v224, 0x358637bd
	s_movk_i32 s63, 0x2000
	v_mov_b64_e32 v[212:213], 0x57f
	s_mov_b32 s4, 0
	s_branch .LBB0_1238

; #define PG8_STAGE(bufoff, gbase, voff) do { _Pragma("unroll") for (int _i = 0; _i < 2; ++_i) \
;         __builtin_amdgcn_global_load_lds((const unsigned*)((const char*)(gbase) + (voff)[_i]), (LAS unsigned*)(lds + (bufoff) + ldsw + _i * 8192), 16, 0, 0); } while (0)
; #define PG8_WAIT_V(n) asm volatile("s_waitcnt vmcnt(" #n ")" ::: "memory")
; #define PG8_BAR __builtin_amdgcn_s_barrier()
; __device__ __forceinline__ void gemm_phase(LAS unsigned char* lds, const Gemm g, const StaticOrder S, const Epi E) {
;     ...
;     unsigned voffA[2], voffB[2];
; #pragma unroll
;     for (int i = 0; i < 2; ++i) { int R, C; stage_rc(tid * 16 + i * 8192, R, C); const int Rb = (R & ~31) + perm32(R & 31);
;         voffA[i] = (unsigned)(R * g.lda + C) * 2u; voffB[i] = (unsigned)(Rb * g.ldb + C) * 2u; }
;     const size_t kstep = (size_t)(BK * 2);
;     const size_t hstepA = (size_t)HALF * g.lda * 2, hstepB = (size_t)HALF * g.ldb * 2;
;     const size_t tstepA = 2 * hstepA, tstepB = 2 * hstepB;
;     const unsigned ldsw = (unsigned)wid * 1024u;
;     const int aoff = lds_byte(wr * 64 + fr, fq * 8), boff = lds_byte(wc * 32 + fr, fq * 8);
;     ...
;     Unit cur, nxt; int ui = 0;
;     if (!S.next(0, cur)) return;
;     cur.seg = 0;
;     const char* cA = gA + (size_t)cur.pm * tstepA + (cur.half == 2 ? hstepA : 0); const char* cB = gB + (size_t)cur.pn * tstepB;
;     PG8_STAGE(PG8_SB(0, 0), cB, voffB); PG8_STAGE(PG8_SB(0, 1), cB + hstepB, voffB); PG8_STAGE(PG8_SA(0, 0), cA, voffA); PG8_STAGE(PG8_SA(0, 1), cA + hstepA, voffA);
;     if (wr == 1) PG8_BAR;
;     PG8_WAIT_V(2); PG8_BAR;
;     PG8_STAGE(PG8_SB(1, 0), cB + kstep, voffB); PG8_STAGE(PG8_SA(1, 0), cA + kstep, voffA); PG8_STAGE(PG8_SB(1, 1), cB + hstepB + kstep, voffB);
;     PG8_WAIT_V(6); PG8_BAR;
; __global__ void __launch_bounds__(NTHREADS, 2) mega_fwd(Args a) {
;     ...
;     if (IN(8)) {
;         pg8::Gemm g{U, (const bf16_t*)(ws + WS_W2_2), FF, FF, FF, S, D}; pg8::StaticOrder so; so.init(S, D, G, (int)blockIdx.x);
;         pg8::Epi E{}; E.mode = pg8::M_RESID; E.base = nullptr; E.outf = a.out; E.scale = 0.5f; E.xb = XB; E.ssq_out = nullptr;
;         pg8::gemm_phase(lds, g, so, E);
.LBB0_1335:
	s_andn2_b64 vcc, exec, s[0:1]
	s_cbranch_vccnz .LBB0_1423
	s_waitcnt vmcnt(0) lgkmcnt(0)
	v_lshrrev_b32_e32 v3, 1, v198
	v_lshrrev_b32_e32 v4, 5, v198
	v_and_b32_e32 v3, 24, v3
	v_and_b32_e32 v4, 4, v4
	v_bfe_u32 v5, v198, 2, 2
	v_lshlrev_b32_e32 v0, 4, v198
	v_and_b32_e32 v1, 32, v198
	v_bfe_u32 v2, v198, 2, 4
	v_or3_b32 v3, v4, v5, v3
	v_lshrrev_b32_e32 v4, 3, v198
	s_movk_i32 s1, 0x70
	v_bitop3_b32 v8, v0, v1, 48 bitop3:0x6c
	v_and_or_b32 v5, v4, s1, v2
	s_movk_i32 s1, 0x60
	v_add_u32_e32 v0, 0x2000, v0
	v_and_or_b32 v4, v4, s1, v3
	v_lshrrev_b32_e32 v0, 7, v0
	s_movk_i32 s1, 0xf0
	s_lshr_b32 s0, s18, 6
	v_and_b32_e32 v9, 64, v198
	v_and_or_b32 v2, v0, s1, v2
	s_movk_i32 s1, 0xe0
	v_or_b32_e32 v1, v8, v9
	v_and_or_b32 v0, v0, s1, v3
	s_lshr_b32 s1, s18, 8
	s_lshl_b32 s33, s0, 10
	s_mul_i32 s13, s34, 0x160000
	v_lshrrev_b32_e32 v1, 1, v1
	v_mul_u32_u24_e32 v4, 0xb00, v4
	s_mul_hi_i32 s12, s34, 0x160000
	s_add_u32 s28, s4, s13
	v_or_b32_e32 v4, v4, v1
	s_addc_u32 s29, s5, s12
	s_add_i32 s36, s33, 0
	v_lshlrev_b32_e32 v158, 1, v4
	s_add_i32 m0, s36, 0x10000
	s_mul_i32 s3, s35, 0x200000
	global_load_lds_dwordx4 v158, s[28:29]
	s_add_i32 m0, s36, 0x12000
	v_mul_u32_u24_e32 v0, 0xb00, v0
	s_mul_hi_i32 s2, s35, 0x200000
	s_add_u32 s30, s20, s3
	v_or_b32_e32 v0, v0, v1
	s_addc_u32 s31, s21, s2
	v_lshlrev_b32_e32 v162, 1, v0
	s_add_u32 s2, s28, 0xb0000
	v_mul_u32_u24_e32 v10, 0x1000, v5
	global_load_lds_dwordx4 v162, s[28:29]
	s_addc_u32 s3, s29, 0
	s_add_i32 m0, s36, 0x14000
	v_or_b32_e32 v5, v1, v10
	v_mul_u32_u24_e32 v11, 0x1000, v2
	global_load_lds_dwordx4 v158, s[2:3]
	s_add_i32 m0, s36, 0x16000
	s_add_i32 s37, s36, 0x2000
	v_lshlrev_b32_e32 v156, 1, v5
	v_or_b32_e32 v2, v11, v1
	global_load_lds_dwordx4 v162, s[2:3]
	s_mov_b32 m0, s36
	s_add_u32 s2, s30, 0x100000
	v_lshlrev_b32_e32 v160, 1, v2
	global_load_lds_dwordx4 v156, s[30:31]
	s_mov_b32 m0, s37
	s_addc_u32 s3, s31, 0
	s_add_i32 s38, s36, 0x4000
	global_load_lds_dwordx4 v160, s[30:31]
	s_mov_b32 m0, s38
	s_add_i32 s39, s36, 0x6000
	global_load_lds_dwordx4 v156, s[2:3]
	s_mov_b32 m0, s39
	v_mov_b32_e32 v159, 0
	global_load_lds_dwordx4 v160, s[2:3]
	v_mov_b32_e32 v163, v159
	v_mov_b32_e32 v157, v159
	v_mov_b32_e32 v161, v159
	s_cmp_eq_u32 s1, 1
	s_mov_b32 s13, 0
	v_lshl_add_u64 v[6:7], s[28:29], 0, v[158:159]
	v_lshl_add_u64 v[4:5], s[28:29], 0, v[162:163]
	v_lshl_add_u64 v[0:1], s[30:31], 0, v[156:157]
	s_cselect_b64 s[14:15], -1, 0
	s_cmp_lg_u32 s1, 1
	v_lshl_add_u64 v[2:3], s[30:31], 0, v[160:161]
	s_cbranch_scc1 .LBB0_1338
	s_barrier

; __device__ __forceinline__ void gemm_phase(LAS unsigned char* lds, const Gemm g, const StaticOrder S, const Epi E) {
;     ...
;         if (cur.seg + 1 < nsegs) { nxt = cur; nxt.seg = cur.seg + 1; has_next = true; } else { has_next = S.next(ui + 1, nxt); nxt.seg = 0; }
;         const char* nA = has_next ? PG8_SEGA(nxt.seg) + (size_t)nxt.pm * tstepA + (nxt.half == 2 ? hstepA : 0) : cA; const char* nB = has_next ? PG8_SEGB(nxt.seg) + (size_t)nxt.pn * tstepB : cB;
.LBB0_1347:
	s_nop 0
	v_cndmask_b32_e64 v0, 0, 1, s[2:3]
	v_cmp_ne_u32_e64 s[0:1], 1, v0
	s_andn2_b64 vcc, exec, s[2:3]
	s_mov_b64 s[24:25], s[30:31]
	s_cbranch_vccnz .LBB0_1349
	s_mul_i32 s3, s51, 0x200000
	s_mul_hi_i32 s2, s51, 0x200000
	s_add_u32 s24, s20, s3
	s_addc_u32 s25, s21, s2

; #define PG8_STAGE(bufoff, gbase, voff) do { _Pragma("unroll") for (int _i = 0; _i < 2; ++_i) \
;         __builtin_amdgcn_global_load_lds((const unsigned*)((const char*)(gbase) + (voff)[_i]), (LAS unsigned*)(lds + (bufoff) + ldsw + _i * 8192), 16, 0, 0); } while (0)
; #define PG8_LDA(dst, b, h) do { _Pragma("unroll") for (int m = 0; m < 4; ++m) _Pragma("unroll") for (int k = 0; k < 2; ++k) dst[m][k] = *(const LAS bf16x8*)(lds + PG8_SA(b, h) + aoff + m * 2048 + k * 1024); } while (0)
; #define PG8_LDB(dst, b, h) do { _Pragma("unroll") for (int n = 0; n < 2; ++n) _Pragma("unroll") for (int k = 0; k < 2; ++k) dst[n][k] = *(const LAS bf16x8*)(lds + PG8_SB(b, h) + boff + n * 2048 + k * 1024); } while (0)
; #define PG8_MMA(ai, bj, At, Bt) do { __builtin_amdgcn_s_setprio(1); _Pragma("unroll") for (int m = 0; m < 4; ++m) _Pragma("unroll") for (int n = 0; n < 2; ++n) _Pragma("unroll") for (int k = 0; k < 2; ++k) \
;         acc[ai][bj][m][n] = __builtin_amdgcn_mfma_f32_16x16x32_bf16(Bt[n][k], At[m][k], acc[ai][bj][m][n], 0, 0, 0); __builtin_amdgcn_s_setprio(0); } while (0)
; #define PG8_BAR __builtin_amdgcn_s_barrier()
; __device__ __forceinline__ void gemm_phase(LAS unsigned char* lds, const Gemm g, const StaticOrder S, const Epi E) {
;     ...
;         for (int t = 0; t < nt; t += 2) {
;             const bool last = (t == nt - 2);
;             const char* a1 = cA + (size_t)(t + 1) * kstep;
;             const char* a2 = last ? nA : cA + (size_t)(t + 2) * kstep; const char* b2 = last ? nB : cB + (size_t)(t + 2) * kstep;
;             const char* a3 = a2 + kstep; const char* b3 = b2 + kstep;
;             PG8_LDB(B0, 0, 0); PG8_LDB(B1, 0, 1); PG8_SCHED; PG8_LDA(At, 0, 0); PG8_STAGE(PG8_SA(1, 1), a1 + hstepA, voffA);
;             PG8_WAIT_V(8); PG8_WAIT_L(0); PG8_BAR; PG8_MMA(0, 0, At, B0); PG8_MMA(0, 1, At, B1); PG8_BAR; PG8_SCHED;
;             if (full) PG8_LDA(At, 0, 1); PG8_STAGE(PG8_SB(0, 0), b2, voffB); PG8_STAGE(PG8_SB(0, 1), b2 + hstepB, voffB); PG8_STAGE(PG8_SA(0, 0), a2, voffA);
;             PG8_WAIT_V(8); PG8_WAIT_L(0); PG8_BAR; if (full) { PG8_MMA(1, 0, At, B0); PG8_MMA(1, 1, At, B1); } PG8_BAR; PG8_SCHED;
;             PG8_LDB(B0, 1, 0); PG8_LDB(B1, 1, 1); PG8_SCHED; PG8_LDA(At, 1, 0); PG8_STAGE(PG8_SA(0, 1), a2 + hstepA, voffA);
;             PG8_WAIT_V(8); PG8_WAIT_L(0); PG8_BAR; PG8_MMA(0, 0, At, B0); PG8_MMA(0, 1, At, B1); PG8_BAR; PG8_SCHED;
.LBB0_1351:
	s_add_u32 s52, s28, 0x100
	s_addc_u32 s53, s29, 0
	s_add_u32 s2, s30, 0x100080
	v_mov_b32_e32 v0, 0
	s_addc_u32 s3, s31, 0
	s_mov_b32 s54, -2
	v_mov_b32_e32 v1, v0
	v_mov_b32_e32 v2, v0
	v_mov_b32_e32 v3, v0
	v_mov_b32_e32 v4, v0
	v_mov_b32_e32 v5, v0
	v_mov_b32_e32 v6, v0
	v_mov_b32_e32 v7, v0
	v_mov_b32_e32 v16, v0
	v_mov_b32_e32 v17, v0
	v_mov_b32_e32 v18, v0
	v_mov_b32_e32 v19, v0
	v_mov_b32_e32 v20, v0
	v_mov_b32_e32 v21, v0
	v_mov_b32_e32 v22, v0
	v_mov_b32_e32 v23, v0
	v_mov_b32_e32 v32, v0
	v_mov_b32_e32 v33, v0
	v_mov_b32_e32 v34, v0
	v_mov_b32_e32 v35, v0
	v_mov_b32_e32 v36, v0
	v_mov_b32_e32 v37, v0
	v_mov_b32_e32 v38, v0
	v_mov_b32_e32 v39, v0
	v_mov_b32_e32 v48, v0
	v_mov_b32_e32 v49, v0
	v_mov_b32_e32 v50, v0
	v_mov_b32_e32 v51, v0
	v_mov_b32_e32 v52, v0
	v_mov_b32_e32 v53, v0
	v_mov_b32_e32 v54, v0
	v_mov_b32_e32 v55, v0
	v_mov_b32_e32 v8, v0
	v_mov_b32_e32 v9, v0
	v_mov_b32_e32 v10, v0
	v_mov_b32_e32 v11, v0
	v_mov_b32_e32 v12, v0
	v_mov_b32_e32 v13, v0
	v_mov_b32_e32 v14, v0
	v_mov_b32_e32 v15, v0
	v_mov_b32_e32 v24, v0
	v_mov_b32_e32 v25, v0
	v_mov_b32_e32 v26, v0
	v_mov_b32_e32 v27, v0
	v_mov_b32_e32 v28, v0
	v_mov_b32_e32 v29, v0
	v_mov_b32_e32 v30, v0
	v_mov_b32_e32 v31, v0
	v_mov_b32_e32 v40, v0
	v_mov_b32_e32 v41, v0
	v_mov_b32_e32 v42, v0
	v_mov_b32_e32 v43, v0
	v_mov_b32_e32 v44, v0
	v_mov_b32_e32 v45, v0
	v_mov_b32_e32 v46, v0
	v_mov_b32_e32 v47, v0
	v_mov_b32_e32 v56, v0
	v_mov_b32_e32 v57, v0
	v_mov_b32_e32 v58, v0
	v_mov_b32_e32 v59, v0
	v_mov_b32_e32 v60, v0
	v_mov_b32_e32 v61, v0
	v_mov_b32_e32 v62, v0
	v_mov_b32_e32 v63, v0
	v_mov_b32_e32 v64, v0
	v_mov_b32_e32 v65, v0
	v_mov_b32_e32 v66, v0
	v_mov_b32_e32 v67, v0
	v_mov_b32_e32 v68, v0
	v_mov_b32_e32 v69, v0
	v_mov_b32_e32 v70, v0
	v_mov_b32_e32 v71, v0
	v_mov_b32_e32 v80, v0
	v_mov_b32_e32 v81, v0
	v_mov_b32_e32 v82, v0
	v_mov_b32_e32 v83, v0
	v_mov_b32_e32 v84, v0
	v_mov_b32_e32 v85, v0
	v_mov_b32_e32 v86, v0
	v_mov_b32_e32 v87, v0
	v_mov_b32_e32 v96, v0
	v_mov_b32_e32 v97, v0
	v_mov_b32_e32 v98, v0
	v_mov_b32_e32 v99, v0
	v_mov_b32_e32 v100, v0
	v_mov_b32_e32 v101, v0
	v_mov_b32_e32 v102, v0
	v_mov_b32_e32 v103, v0
	v_mov_b32_e32 v112, v0
	v_mov_b32_e32 v113, v0
	v_mov_b32_e32 v114, v0
	v_mov_b32_e32 v115, v0
	v_mov_b32_e32 v116, v0
	v_mov_b32_e32 v117, v0
	v_mov_b32_e32 v118, v0
	v_mov_b32_e32 v119, v0
	v_mov_b32_e32 v72, v0
	v_mov_b32_e32 v73, v0
	v_mov_b32_e32 v74, v0
	v_mov_b32_e32 v75, v0
	v_mov_b32_e32 v76, v0
	v_mov_b32_e32 v77, v0
	v_mov_b32_e32 v78, v0
	v_mov_b32_e32 v79, v0
	v_mov_b32_e32 v88, v0
	v_mov_b32_e32 v89, v0
	v_mov_b32_e32 v90, v0
	v_mov_b32_e32 v91, v0
	v_mov_b32_e32 v92, v0
	v_mov_b32_e32 v93, v0
	v_mov_b32_e32 v94, v0
	v_mov_b32_e32 v95, v0
	v_mov_b32_e32 v104, v0
	v_mov_b32_e32 v105, v0
	v_mov_b32_e32 v106, v0
	v_mov_b32_e32 v107, v0
	v_mov_b32_e32 v108, v0
	v_mov_b32_e32 v109, v0
	v_mov_b32_e32 v110, v0
	v_mov_b32_e32 v111, v0
	v_mov_b32_e32 v120, v0
	v_mov_b32_e32 v121, v0
	v_mov_b32_e32 v122, v0
	v_mov_b32_e32 v123, v0
	v_mov_b32_e32 v124, v0
	v_mov_b32_e32 v125, v0
	v_mov_b32_e32 v126, v0
	v_mov_b32_e32 v127, v0
.LBB0_1352:
	ds_read_b128 v[128:131], v193
	ds_read_b128 v[132:135], v193 offset:1024
	ds_read_b128 v[136:139], v193 offset:2048
	ds_read_b128 v[140:143], v193 offset:3072
	ds_read_b128 v[144:147], v194
	ds_read_b128 v[148:151], v194 offset:1024
	ds_read_b128 v[152:155], v194 offset:2048
	ds_read_b128 v[172:175], v194 offset:3072
	s_add_u32 s28, s2, 0xfff00080
	s_addc_u32 s29, s3, -1
	s_cmp_eq_u32 s54, 40
	s_cselect_b32 s31, s25, s29
	s_cselect_b32 s30, s24, s28
	s_cselect_b32 s29, s27, s53
	s_cselect_b32 s28, s26, s52
	v_lshl_add_u64 v[188:189], s[2:3], 0, v[166:167]
	s_add_i32 m0, s36, 0xc000
	ds_read_b128 v[176:179], v195
	ds_read_b128 v[180:183], v195 offset:1024
	ds_read_b128 v[184:187], v195 offset:2048
	ds_read_b128 v[196:199], v195 offset:3072
	ds_read_b128 v[200:203], v195 offset:4096
	ds_read_b128 v[204:207], v195 offset:5120
	ds_read_b128 v[208:211], v195 offset:6144
	ds_read_b128 v[212:215], v195 offset:7168
	global_load_lds_dwordx4 v[188:189], off
	v_lshl_add_u64 v[188:189], s[2:3], 0, v[164:165]
	s_add_i32 m0, s36, 0xe000
	s_nop 0
	global_load_lds_dwordx4 v[188:189], off
	s_waitcnt vmcnt(8)
	s_waitcnt lgkmcnt(0)
	s_barrier
	s_setprio 1
	s_waitcnt lgkmcnt(0)
	v_mfma_f32_16x16x32_bf16 v[124:127], v[128:131], v[176:179], v[124:127]
	v_mfma_f32_16x16x32_bf16 v[120:123], v[136:139], v[176:179], v[120:123]
	v_mfma_f32_16x16x32_bf16 v[108:111], v[128:131], v[184:187], v[108:111]
	v_mfma_f32_16x16x32_bf16 v[104:107], v[136:139], v[184:187], v[104:107]
	v_mfma_f32_16x16x32_bf16 v[92:95], v[128:131], v[200:203], v[92:95]
	v_mfma_f32_16x16x32_bf16 v[88:91], v[136:139], v[200:203], v[88:91]
	v_mfma_f32_16x16x32_bf16 v[76:79], v[128:131], v[208:211], v[76:79]
	v_mfma_f32_16x16x32_bf16 v[72:75], v[136:139], v[208:211], v[72:75]
	v_mfma_f32_16x16x32_bf16 v[124:127], v[132:135], v[180:183], v[124:127]
	v_mfma_f32_16x16x32_bf16 v[120:123], v[140:143], v[180:183], v[120:123]
	v_mfma_f32_16x16x32_bf16 v[108:111], v[132:135], v[196:199], v[108:111]
	v_mfma_f32_16x16x32_bf16 v[104:107], v[140:143], v[196:199], v[104:107]
	v_mfma_f32_16x16x32_bf16 v[92:95], v[132:135], v[204:207], v[92:95]
	v_mfma_f32_16x16x32_bf16 v[88:91], v[140:143], v[204:207], v[88:91]
	v_mfma_f32_16x16x32_bf16 v[76:79], v[132:135], v[212:215], v[76:79]
	v_mfma_f32_16x16x32_bf16 v[72:75], v[140:143], v[212:215], v[72:75]
	s_setprio 0
	s_setprio 1
	v_mfma_f32_16x16x32_bf16 v[116:119], v[144:147], v[176:179], v[116:119]
	v_mfma_f32_16x16x32_bf16 v[112:115], v[152:155], v[176:179], v[112:115]
	v_mfma_f32_16x16x32_bf16 v[100:103], v[144:147], v[184:187], v[100:103]
	v_mfma_f32_16x16x32_bf16 v[96:99], v[152:155], v[184:187], v[96:99]
	v_mfma_f32_16x16x32_bf16 v[84:87], v[144:147], v[200:203], v[84:87]
	v_mfma_f32_16x16x32_bf16 v[80:83], v[152:155], v[200:203], v[80:83]
	v_mfma_f32_16x16x32_bf16 v[68:71], v[144:147], v[208:211], v[68:71]
	v_mfma_f32_16x16x32_bf16 v[64:67], v[152:155], v[208:211], v[64:67]
	v_mfma_f32_16x16x32_bf16 v[116:119], v[148:151], v[180:183], v[116:119]
	v_mfma_f32_16x16x32_bf16 v[112:115], v[172:175], v[180:183], v[112:115]
	v_mfma_f32_16x16x32_bf16 v[100:103], v[148:151], v[196:199], v[100:103]
	v_mfma_f32_16x16x32_bf16 v[96:99], v[172:175], v[196:199], v[96:99]
	v_mfma_f32_16x16x32_bf16 v[84:87], v[148:151], v[204:207], v[84:87]
	v_mfma_f32_16x16x32_bf16 v[80:83], v[172:175], v[204:207], v[80:83]
	v_mfma_f32_16x16x32_bf16 v[68:71], v[148:151], v[212:215], v[68:71]
	v_mfma_f32_16x16x32_bf16 v[64:67], v[172:175], v[212:215], v[64:67]
	s_setprio 0
	s_barrier
; #define PG8_STAGE(bufoff, gbase, voff) do { _Pragma("unroll") for (int _i = 0; _i < 2; ++_i) \
;         __builtin_amdgcn_global_load_lds((const unsigned*)((const char*)(gbase) + (voff)[_i]), (LAS unsigned*)(lds + (bufoff) + ldsw + _i * 8192), 16, 0, 0); } while (0)
; #define PG8_LDA(dst, b, h) do { _Pragma("unroll") for (int m = 0; m < 4; ++m) _Pragma("unroll") for (int k = 0; k < 2; ++k) dst[m][k] = *(const LAS bf16x8*)(lds + PG8_SA(b, h) + aoff + m * 2048 + k * 1024); } while (0)
; #define PG8_LDB(dst, b, h) do { _Pragma("unroll") for (int n = 0; n < 2; ++n) _Pragma("unroll") for (int k = 0; k < 2; ++k) dst[n][k] = *(const LAS bf16x8*)(lds + PG8_SB(b, h) + boff + n * 2048 + k * 1024); } while (0)
; #define PG8_MMA(ai, bj, At, Bt) do { __builtin_amdgcn_s_setprio(1); _Pragma("unroll") for (int m = 0; m < 4; ++m) _Pragma("unroll") for (int n = 0; n < 2; ++n) _Pragma("unroll") for (int k = 0; k < 2; ++k) \
;         acc[ai][bj][m][n] = __builtin_amdgcn_mfma_f32_16x16x32_bf16(Bt[n][k], At[m][k], acc[ai][bj][m][n], 0, 0, 0); __builtin_amdgcn_s_setprio(0); } while (0)
; #define PG8_WAIT_V(n) asm volatile("s_waitcnt vmcnt(" #n ")" ::: "memory")
; #define PG8_WAIT_L(n) asm volatile("s_waitcnt lgkmcnt(" #n ")" ::: "memory")
; #define PG8_BAR __builtin_amdgcn_s_barrier()
; #define PG8_SCHED __builtin_amdgcn_sched_barrier(0)
; __device__ __forceinline__ void gemm_phase(LAS unsigned char* lds, const Gemm g, const StaticOrder S, const Epi E) {
;     ...
;             if (full) PG8_LDA(At, 0, 1); PG8_STAGE(PG8_SB(0, 0), b2, voffB); PG8_STAGE(PG8_SB(0, 1), b2 + hstepB, voffB); PG8_STAGE(PG8_SA(0, 0), a2, voffA);
;             PG8_WAIT_V(8); PG8_WAIT_L(0); PG8_BAR; if (full) { PG8_MMA(1, 0, At, B0); PG8_MMA(1, 1, At, B1); } PG8_BAR; PG8_SCHED;
;             PG8_LDB(B0, 1, 0); PG8_LDB(B1, 1, 1); PG8_SCHED; PG8_LDA(At, 1, 0); PG8_STAGE(PG8_SA(0, 1), a2 + hstepA, voffA);
;             PG8_WAIT_V(8); PG8_WAIT_L(0); PG8_BAR; PG8_MMA(0, 0, At, B0); PG8_MMA(0, 1, At, B1); PG8_BAR; PG8_SCHED;
;             if (full) PG8_LDA(At, 1, 1); PG8_STAGE(PG8_SB(1, 0), b3, voffB); PG8_STAGE(PG8_SB(1, 1), b3 + hstepB, voffB); PG8_STAGE(PG8_SA(1, 0), a3, voffA);
	s_add_i32 s55, s47, s33
	v_lshl_add_u64 v[188:189], s[28:29], 0, v[158:159]
	s_mov_b32 m0, s55
	ds_read_b128 v[176:179], v195 offset:16384
	ds_read_b128 v[180:183], v195 offset:17408
	ds_read_b128 v[184:187], v195 offset:18432
	ds_read_b128 v[196:199], v195 offset:19456
	ds_read_b128 v[200:203], v195 offset:20480
	ds_read_b128 v[204:207], v195 offset:21504
	ds_read_b128 v[208:211], v195 offset:22528
	ds_read_b128 v[212:215], v195 offset:23552
	global_load_lds_dwordx4 v[188:189], off
	s_add_i32 m0, s55, 0x2000
	s_add_u32 s56, s28, 0xb0000
	v_lshl_add_u64 v[216:217], s[28:29], 0, v[162:163]
	s_addc_u32 s57, s29, 0
	s_add_i32 s55, s48, s33
	global_load_lds_dwordx4 v[216:217], off
	v_lshl_add_u64 v[218:219], s[56:57], 0, v[158:159]
	s_mov_b32 m0, s55
	v_lshl_add_u64 v[220:221], s[30:31], 0, v[160:161]
	global_load_lds_dwordx4 v[218:219], off
	v_lshl_add_u64 v[218:219], s[56:57], 0, v[162:163]
	s_add_i32 m0, s55, 0x2000
	s_nop 0
	global_load_lds_dwordx4 v[218:219], off
	v_lshl_add_u64 v[218:219], s[30:31], 0, v[156:157]
	s_mov_b32 m0, s36
	s_nop 0
	global_load_lds_dwordx4 v[218:219], off
	s_mov_b32 m0, s37
	s_nop 0
	global_load_lds_dwordx4 v[220:221], off
	s_waitcnt vmcnt(8)
	s_waitcnt lgkmcnt(0)
	s_barrier
	s_setprio 1
	s_waitcnt lgkmcnt(0)
	v_mfma_f32_16x16x32_bf16 v[60:63], v[128:131], v[176:179], v[60:63]
	v_mfma_f32_16x16x32_bf16 v[56:59], v[136:139], v[176:179], v[56:59]
	v_mfma_f32_16x16x32_bf16 v[44:47], v[128:131], v[184:187], v[44:47]
	v_mfma_f32_16x16x32_bf16 v[40:43], v[136:139], v[184:187], v[40:43]
	v_mfma_f32_16x16x32_bf16 v[28:31], v[128:131], v[200:203], v[28:31]
	v_mfma_f32_16x16x32_bf16 v[24:27], v[136:139], v[200:203], v[24:27]
	v_mfma_f32_16x16x32_bf16 v[12:15], v[128:131], v[208:211], v[12:15]
	v_mfma_f32_16x16x32_bf16 v[8:11], v[136:139], v[208:211], v[8:11]
	v_mfma_f32_16x16x32_bf16 v[60:63], v[132:135], v[180:183], v[60:63]
	v_mfma_f32_16x16x32_bf16 v[56:59], v[140:143], v[180:183], v[56:59]
	v_mfma_f32_16x16x32_bf16 v[44:47], v[132:135], v[196:199], v[44:47]
	v_mfma_f32_16x16x32_bf16 v[40:43], v[140:143], v[196:199], v[40:43]
	v_mfma_f32_16x16x32_bf16 v[28:31], v[132:135], v[204:207], v[28:31]
	v_mfma_f32_16x16x32_bf16 v[24:27], v[140:143], v[204:207], v[24:27]
	v_mfma_f32_16x16x32_bf16 v[12:15], v[132:135], v[212:215], v[12:15]
	v_mfma_f32_16x16x32_bf16 v[8:11], v[140:143], v[212:215], v[8:11]
	s_setprio 0
	s_setprio 1
	v_mfma_f32_16x16x32_bf16 v[52:55], v[144:147], v[176:179], v[52:55]
	v_mfma_f32_16x16x32_bf16 v[48:51], v[152:155], v[176:179], v[48:51]
	v_mfma_f32_16x16x32_bf16 v[36:39], v[144:147], v[184:187], v[36:39]
	v_mfma_f32_16x16x32_bf16 v[32:35], v[152:155], v[184:187], v[32:35]
	v_mfma_f32_16x16x32_bf16 v[20:23], v[144:147], v[200:203], v[20:23]
	v_mfma_f32_16x16x32_bf16 v[16:19], v[152:155], v[200:203], v[16:19]
	v_mfma_f32_16x16x32_bf16 v[4:7], v[144:147], v[208:211], v[4:7]
	v_mfma_f32_16x16x32_bf16 v[0:3], v[152:155], v[208:211], v[0:3]
	v_mfma_f32_16x16x32_bf16 v[52:55], v[148:151], v[180:183], v[52:55]
	v_mfma_f32_16x16x32_bf16 v[48:51], v[172:175], v[180:183], v[48:51]
	v_mfma_f32_16x16x32_bf16 v[36:39], v[148:151], v[196:199], v[36:39]
	v_mfma_f32_16x16x32_bf16 v[32:35], v[172:175], v[196:199], v[32:35]
	v_mfma_f32_16x16x32_bf16 v[20:23], v[148:151], v[204:207], v[20:23]
	v_mfma_f32_16x16x32_bf16 v[16:19], v[172:175], v[204:207], v[16:19]
	v_mfma_f32_16x16x32_bf16 v[4:7], v[148:151], v[212:215], v[4:7]
	v_mfma_f32_16x16x32_bf16 v[0:3], v[172:175], v[212:215], v[0:3]
	s_setprio 0
	s_barrier
	s_add_i32 s55, 0, 0x18000
	s_add_i32 s56, 0, 0x1c000
	v_add_u32_e32 v140, s55, v192
	v_add_u32_e32 v172, s56, v192
	ds_read_b128 v[128:131], v140
	ds_read_b128 v[132:135], v140 offset:1024
	ds_read_b128 v[136:139], v140 offset:2048
	ds_read_b128 v[140:143], v140 offset:3072
	ds_read_b128 v[144:147], v172
	ds_read_b128 v[148:151], v172 offset:1024
	ds_read_b128 v[152:155], v172 offset:2048
	ds_read_b128 v[172:175], v172 offset:3072
	s_add_u32 s30, s30, 0x100000
	s_addc_u32 s31, s31, 0
	s_mov_b32 m0, s38
	v_lshl_add_u64 v[222:223], s[30:31], 0, v[156:157]
	ds_read_b128 v[176:179], v195 offset:32768
	ds_read_b128 v[180:183], v195 offset:33792
	ds_read_b128 v[184:187], v195 offset:34816
	ds_read_b128 v[196:199], v195 offset:35840
	ds_read_b128 v[200:203], v195 offset:36864
	ds_read_b128 v[204:207], v195 offset:37888
	ds_read_b128 v[208:211], v195 offset:38912
	ds_read_b128 v[212:215], v195 offset:39936
	global_load_lds_dwordx4 v[222:223], off
	v_lshl_add_u64 v[222:223], s[30:31], 0, v[160:161]
	s_mov_b32 m0, s39
	s_nop 0
	global_load_lds_dwordx4 v[222:223], off
	s_waitcnt vmcnt(8)
	s_waitcnt lgkmcnt(0)
	s_barrier
; #define PG8_STAGE(bufoff, gbase, voff) do { _Pragma("unroll") for (int _i = 0; _i < 2; ++_i) \
;         __builtin_amdgcn_global_load_lds((const unsigned*)((const char*)(gbase) + (voff)[_i]), (LAS unsigned*)(lds + (bufoff) + ldsw + _i * 8192), 16, 0, 0); } while (0)
; #define PG8_LDA(dst, b, h) do { _Pragma("unroll") for (int m = 0; m < 4; ++m) _Pragma("unroll") for (int k = 0; k < 2; ++k) dst[m][k] = *(const LAS bf16x8*)(lds + PG8_SA(b, h) + aoff + m * 2048 + k * 1024); } while (0)
; #define PG8_LDB(dst, b, h) do { _Pragma("unroll") for (int n = 0; n < 2; ++n) _Pragma("unroll") for (int k = 0; k < 2; ++k) dst[n][k] = *(const LAS bf16x8*)(lds + PG8_SB(b, h) + boff + n * 2048 + k * 1024); } while (0)
; #define PG8_MMA(ai, bj, At, Bt) do { __builtin_amdgcn_s_setprio(1); _Pragma("unroll") for (int m = 0; m < 4; ++m) _Pragma("unroll") for (int n = 0; n < 2; ++n) _Pragma("unroll") for (int k = 0; k < 2; ++k) \
;         acc[ai][bj][m][n] = __builtin_amdgcn_mfma_f32_16x16x32_bf16(Bt[n][k], At[m][k], acc[ai][bj][m][n], 0, 0, 0); __builtin_amdgcn_s_setprio(0); } while (0)
; #define PG8_WAIT_V(n) asm volatile("s_waitcnt vmcnt(" #n ")" ::: "memory")
; #define PG8_WAIT_L(n) asm volatile("s_waitcnt lgkmcnt(" #n ")" ::: "memory")
; #define PG8_BAR __builtin_amdgcn_s_barrier()
; #define PG8_SCHED __builtin_amdgcn_sched_barrier(0)
; __device__ __forceinline__ void gemm_phase(LAS unsigned char* lds, const Gemm g, const StaticOrder S, const Epi E) {
;     ...
;             PG8_LDB(B0, 1, 0); PG8_LDB(B1, 1, 1); PG8_SCHED; PG8_LDA(At, 1, 0); PG8_STAGE(PG8_SA(0, 1), a2 + hstepA, voffA);
;             PG8_WAIT_V(8); PG8_WAIT_L(0); PG8_BAR; PG8_MMA(0, 0, At, B0); PG8_MMA(0, 1, At, B1); PG8_BAR; PG8_SCHED;
;             if (full) PG8_LDA(At, 1, 1); PG8_STAGE(PG8_SB(1, 0), b3, voffB); PG8_STAGE(PG8_SB(1, 1), b3 + hstepB, voffB); PG8_STAGE(PG8_SA(1, 0), a3, voffA);
;             PG8_WAIT_V(8); PG8_WAIT_L(0); PG8_BAR; if (full) { PG8_MMA(1, 0, At, B0); PG8_MMA(1, 1, At, B1); } PG8_BAR; PG8_SCHED;
;         }
	s_setprio 1
	s_waitcnt lgkmcnt(0)
	v_mfma_f32_16x16x32_bf16 v[124:127], v[128:131], v[176:179], v[124:127]
	v_mfma_f32_16x16x32_bf16 v[120:123], v[136:139], v[176:179], v[120:123]
	v_mfma_f32_16x16x32_bf16 v[108:111], v[128:131], v[184:187], v[108:111]
	v_mfma_f32_16x16x32_bf16 v[104:107], v[136:139], v[184:187], v[104:107]
	v_mfma_f32_16x16x32_bf16 v[92:95], v[128:131], v[200:203], v[92:95]
	v_mfma_f32_16x16x32_bf16 v[88:91], v[136:139], v[200:203], v[88:91]
	v_mfma_f32_16x16x32_bf16 v[76:79], v[128:131], v[208:211], v[76:79]
	v_mfma_f32_16x16x32_bf16 v[72:75], v[136:139], v[208:211], v[72:75]
	v_mfma_f32_16x16x32_bf16 v[124:127], v[132:135], v[180:183], v[124:127]
	v_mfma_f32_16x16x32_bf16 v[120:123], v[140:143], v[180:183], v[120:123]
	v_mfma_f32_16x16x32_bf16 v[108:111], v[132:135], v[196:199], v[108:111]
	v_mfma_f32_16x16x32_bf16 v[104:107], v[140:143], v[196:199], v[104:107]
	v_mfma_f32_16x16x32_bf16 v[92:95], v[132:135], v[204:207], v[92:95]
	v_mfma_f32_16x16x32_bf16 v[88:91], v[140:143], v[204:207], v[88:91]
	v_mfma_f32_16x16x32_bf16 v[76:79], v[132:135], v[212:215], v[76:79]
	v_mfma_f32_16x16x32_bf16 v[72:75], v[140:143], v[212:215], v[72:75]
	s_setprio 0
	s_setprio 1
	v_mfma_f32_16x16x32_bf16 v[116:119], v[144:147], v[176:179], v[116:119]
	v_mfma_f32_16x16x32_bf16 v[112:115], v[152:155], v[176:179], v[112:115]
	v_mfma_f32_16x16x32_bf16 v[100:103], v[144:147], v[184:187], v[100:103]
	v_mfma_f32_16x16x32_bf16 v[96:99], v[152:155], v[184:187], v[96:99]
	v_mfma_f32_16x16x32_bf16 v[84:87], v[144:147], v[200:203], v[84:87]
	v_mfma_f32_16x16x32_bf16 v[80:83], v[152:155], v[200:203], v[80:83]
	v_mfma_f32_16x16x32_bf16 v[68:71], v[144:147], v[208:211], v[68:71]
	v_mfma_f32_16x16x32_bf16 v[64:67], v[152:155], v[208:211], v[64:67]
	v_mfma_f32_16x16x32_bf16 v[116:119], v[148:151], v[180:183], v[116:119]
	v_mfma_f32_16x16x32_bf16 v[112:115], v[172:175], v[180:183], v[112:115]
	v_mfma_f32_16x16x32_bf16 v[100:103], v[148:151], v[196:199], v[100:103]
	v_mfma_f32_16x16x32_bf16 v[96:99], v[172:175], v[196:199], v[96:99]
	v_mfma_f32_16x16x32_bf16 v[84:87], v[148:151], v[204:207], v[84:87]
	v_mfma_f32_16x16x32_bf16 v[80:83], v[172:175], v[204:207], v[80:83]
	v_mfma_f32_16x16x32_bf16 v[68:71], v[148:151], v[212:215], v[68:71]
	v_mfma_f32_16x16x32_bf16 v[64:67], v[172:175], v[212:215], v[64:67]
	s_setprio 0
	s_barrier
	s_add_i32 s30, s55, s33
	v_lshl_add_u64 v[188:189], v[188:189], 0, s[16:17]
	s_mov_b32 m0, s30
	ds_read_b128 v[176:179], v195 offset:49152
	ds_read_b128 v[180:183], v195 offset:50176
	ds_read_b128 v[184:187], v195 offset:51200
	ds_read_b128 v[196:199], v195 offset:52224
	ds_read_b128 v[200:203], v195 offset:53248
	ds_read_b128 v[204:207], v195 offset:54272
	ds_read_b128 v[208:211], v195 offset:55296
	ds_read_b128 v[212:215], v195 offset:56320
	global_load_lds_dwordx4 v[188:189], off
	s_add_i32 m0, s30, 0x2000
	s_add_u32 s28, s28, 0xb0080
	v_lshl_add_u64 v[188:189], v[216:217], 0, s[16:17]
	s_addc_u32 s29, s29, 0
	s_add_i32 s30, s56, s33
	global_load_lds_dwordx4 v[188:189], off
	v_lshl_add_u64 v[188:189], s[28:29], 0, v[158:159]
	s_mov_b32 m0, s30
	s_nop 0
	global_load_lds_dwordx4 v[188:189], off
	v_lshl_add_u64 v[188:189], s[28:29], 0, v[162:163]
	s_add_i32 m0, s30, 0x2000
	s_nop 0
	global_load_lds_dwordx4 v[188:189], off
	v_lshl_add_u64 v[188:189], v[218:219], 0, s[16:17]
	s_mov_b32 m0, s41
	s_nop 0
	global_load_lds_dwordx4 v[188:189], off
	v_lshl_add_u64 v[188:189], v[220:221], 0, s[16:17]
	s_mov_b32 m0, s42
	s_nop 0
	global_load_lds_dwordx4 v[188:189], off
	s_waitcnt vmcnt(8)
	s_waitcnt lgkmcnt(0)
	s_barrier
	s_setprio 1
	s_waitcnt lgkmcnt(0)
	v_mfma_f32_16x16x32_bf16 v[60:63], v[128:131], v[176:179], v[60:63]
	v_mfma_f32_16x16x32_bf16 v[56:59], v[136:139], v[176:179], v[56:59]
	v_mfma_f32_16x16x32_bf16 v[44:47], v[128:131], v[184:187], v[44:47]
	v_mfma_f32_16x16x32_bf16 v[40:43], v[136:139], v[184:187], v[40:43]
	v_mfma_f32_16x16x32_bf16 v[28:31], v[128:131], v[200:203], v[28:31]
	v_mfma_f32_16x16x32_bf16 v[24:27], v[136:139], v[200:203], v[24:27]
	v_mfma_f32_16x16x32_bf16 v[12:15], v[128:131], v[208:211], v[12:15]
	v_mfma_f32_16x16x32_bf16 v[8:11], v[136:139], v[208:211], v[8:11]
	v_mfma_f32_16x16x32_bf16 v[60:63], v[132:135], v[180:183], v[60:63]
	v_mfma_f32_16x16x32_bf16 v[56:59], v[140:143], v[180:183], v[56:59]
	v_mfma_f32_16x16x32_bf16 v[44:47], v[132:135], v[196:199], v[44:47]
	v_mfma_f32_16x16x32_bf16 v[40:43], v[140:143], v[196:199], v[40:43]
	v_mfma_f32_16x16x32_bf16 v[28:31], v[132:135], v[204:207], v[28:31]
	v_mfma_f32_16x16x32_bf16 v[24:27], v[140:143], v[204:207], v[24:27]
	v_mfma_f32_16x16x32_bf16 v[12:15], v[132:135], v[212:215], v[12:15]
	v_mfma_f32_16x16x32_bf16 v[8:11], v[140:143], v[212:215], v[8:11]
	s_setprio 0
	s_setprio 1
	v_mfma_f32_16x16x32_bf16 v[52:55], v[144:147], v[176:179], v[52:55]
	v_mfma_f32_16x16x32_bf16 v[48:51], v[152:155], v[176:179], v[48:51]
	v_mfma_f32_16x16x32_bf16 v[36:39], v[144:147], v[184:187], v[36:39]
	v_mfma_f32_16x16x32_bf16 v[32:35], v[152:155], v[184:187], v[32:35]
	v_mfma_f32_16x16x32_bf16 v[20:23], v[144:147], v[200:203], v[20:23]
	v_mfma_f32_16x16x32_bf16 v[16:19], v[152:155], v[200:203], v[16:19]
	v_mfma_f32_16x16x32_bf16 v[4:7], v[144:147], v[208:211], v[4:7]
	v_mfma_f32_16x16x32_bf16 v[0:3], v[152:155], v[208:211], v[0:3]
	v_mfma_f32_16x16x32_bf16 v[52:55], v[148:151], v[180:183], v[52:55]
	v_mfma_f32_16x16x32_bf16 v[48:51], v[172:175], v[180:183], v[48:51]
	v_mfma_f32_16x16x32_bf16 v[36:39], v[148:151], v[196:199], v[36:39]
	v_mfma_f32_16x16x32_bf16 v[32:35], v[172:175], v[196:199], v[32:35]
	v_mfma_f32_16x16x32_bf16 v[20:23], v[148:151], v[204:207], v[20:23]
	v_mfma_f32_16x16x32_bf16 v[16:19], v[172:175], v[204:207], v[16:19]
	v_mfma_f32_16x16x32_bf16 v[4:7], v[148:151], v[212:215], v[4:7]
	v_mfma_f32_16x16x32_bf16 v[0:3], v[172:175], v[212:215], v[0:3]
	s_setprio 0
	s_barrier
	s_add_i32 s54, s54, 2
	s_add_u32 s52, s52, 0x100
	s_addc_u32 s53, s53, 0
	s_add_u32 s2, s2, 0x100
	s_addc_u32 s3, s3, 0
	s_cmp_gt_u32 s54, 41
	s_cbranch_scc0 .LBB0_1352
	s_and_b64 vcc, exec, s[18:19]
	s_cbranch_vccz .LBB0_1355
	s_barrier
